# v18 + B-fragment read hoist (phases 1/5 into the preceding MMA segment, counted vmcnt(8)) applied to the pair-mix, w_out and ff2 K-loops as well
# speedup vs baseline: 1.0033x; 1.0033x over previous
; #define PG8_STAGE(bufoff, gbase, voff) do { _Pragma("unroll") for (int _i = 0; _i < 2; ++_i) \
;         __builtin_amdgcn_global_load_lds((const unsigned*)((const char*)(gbase) + (voff)[_i]), (LAS unsigned*)(lds + (bufoff) + ldsw + _i * 8192), 16, 0, 0); } while (0)
; #define PG8_LDA(dst, b, h) do { _Pragma("unroll") for (int m = 0; m < 4; ++m) _Pragma("unroll") for (int k = 0; k < 2; ++k) dst[m][k] = *(const LAS bf16x8*)(lds + PG8_SA(b, h) + aoff + m * 2048 + k * 1024); } while (0)
; #define PG8_LDB(dst, b, h) do { _Pragma("unroll") for (int n = 0; n < 2; ++n) _Pragma("unroll") for (int k = 0; k < 2; ++k) dst[n][k] = *(const LAS bf16x8*)(lds + PG8_SB(b, h) + boff + n * 2048 + k * 1024); } while (0)
; #define PG8_MMA(ai, bj, At, Bt) do { __builtin_amdgcn_s_setprio(1); _Pragma("unroll") for (int m = 0; m < 4; ++m) _Pragma("unroll") for (int n = 0; n < 2; ++n) _Pragma("unroll") for (int k = 0; k < 2; ++k) \
;         acc[ai][bj][m][n] = __builtin_amdgcn_mfma_f32_16x16x32_bf16(Bt[n][k], At[m][k], acc[ai][bj][m][n], 0, 0, 0); __builtin_amdgcn_s_setprio(0); } while (0)
; #define PG8_WAIT_L(n) asm volatile("s_waitcnt lgkmcnt(" #n ")" ::: "memory")
; #define PG8_BAR __builtin_amdgcn_s_barrier()
; #define PG8_SCHED __builtin_amdgcn_sched_barrier(0)
; template <class Epi>
; __device__ __forceinline__ void gemm_phase(LAS unsigned char* lds, const Gemm g, const StaticOrder& S, const Epi& E) {
;     ...
;         for (int t = 0; t < nt; t += 2) {
;             const bool last = (t == nt - 2);
;             const char* a1 = cA + (size_t)(t + 1) * kstep;
;             const char* a2 = last ? nA : cA + (size_t)(t + 2) * kstep; const char* b2 = last ? nB : cB + (size_t)(t + 2) * kstep;
;             const char* a3 = a2 + kstep; const char* b3 = b2 + kstep;
;             PG8_LDB(B0, 0, 0); PG8_SCHED; PG8_LDA(At, 0, 0); PG8_STAGE(PG8_SA(1, 1), a1 + hA, voffA);
;             PG8_WAIT_L(8); PG8_BAR; PG8_WAIT_L(0); PG8_MMA(0, 0, At, B0); PG8_BAR; PG8_SCHED;
;     ...
;         if (!(Epi::PAIRS && cur.alt == 0)) {
; #pragma unroll
;         for (int a = 0; a < 2; ++a)
; #pragma unroll
;             for (int b = 0; b < 2; ++b)
; #pragma unroll
;                 for (int m = 0; m < 4; ++m)
; #pragma unroll
;                     for (int n = 0; n < 2; ++n) acc[a][b][m][n] = (f32x4){0.f, 0.f, 0.f, 0.f}; }
;         cur = nxt; cA = nA; cB = nB; ++ui;
.LBB0_62:
	s_add_i32 s59, s33, -2
	s_add_u32 s61, s64, 0x100
	v_mov_b32_e32 v2, 0
	s_addc_u32 s97, s65, 0
	s_mov_b32 s66, 0
	v_add_u32_e32 v218, 0x10000, v188
	ds_read_b128 v[130:133], v218
	ds_read_b128 v[134:137], v218 offset:1024
	ds_read_b128 v[138:141], v218 offset:2048
	ds_read_b128 v[142:145], v218 offset:3072
	v_mov_b32_e32 v3, v2
	v_mov_b32_e32 v4, v2
	v_mov_b32_e32 v5, v2
	v_mov_b32_e32 v6, v2
	v_mov_b32_e32 v7, v2
	v_mov_b32_e32 v8, v2
	v_mov_b32_e32 v9, v2
	v_mov_b32_e32 v18, v2
	v_mov_b32_e32 v19, v2
	v_mov_b32_e32 v20, v2
	v_mov_b32_e32 v21, v2
	v_mov_b32_e32 v22, v2
	v_mov_b32_e32 v23, v2
	v_mov_b32_e32 v24, v2
	v_mov_b32_e32 v25, v2
	v_mov_b32_e32 v34, v2
	v_mov_b32_e32 v35, v2
	v_mov_b32_e32 v36, v2
	v_mov_b32_e32 v37, v2
	v_mov_b32_e32 v38, v2
	v_mov_b32_e32 v39, v2
	v_mov_b32_e32 v40, v2
	v_mov_b32_e32 v41, v2
	v_mov_b32_e32 v50, v2
	v_mov_b32_e32 v51, v2
	v_mov_b32_e32 v52, v2
	v_mov_b32_e32 v53, v2
	v_mov_b32_e32 v54, v2
	v_mov_b32_e32 v55, v2
	v_mov_b32_e32 v56, v2
	v_mov_b32_e32 v57, v2
	v_mov_b32_e32 v10, v2
	v_mov_b32_e32 v11, v2
	v_mov_b32_e32 v12, v2
	v_mov_b32_e32 v13, v2
	v_mov_b32_e32 v14, v2
	v_mov_b32_e32 v15, v2
	v_mov_b32_e32 v16, v2
	v_mov_b32_e32 v17, v2
	v_mov_b32_e32 v26, v2
	v_mov_b32_e32 v27, v2
	v_mov_b32_e32 v28, v2
	v_mov_b32_e32 v29, v2
	v_mov_b32_e32 v30, v2
	v_mov_b32_e32 v31, v2
	v_mov_b32_e32 v32, v2
	v_mov_b32_e32 v33, v2
	v_mov_b32_e32 v42, v2
	v_mov_b32_e32 v43, v2
	v_mov_b32_e32 v44, v2
	v_mov_b32_e32 v45, v2
	v_mov_b32_e32 v46, v2
	v_mov_b32_e32 v47, v2
	v_mov_b32_e32 v48, v2
	v_mov_b32_e32 v49, v2
	v_mov_b32_e32 v58, v2
	v_mov_b32_e32 v59, v2
	v_mov_b32_e32 v60, v2
	v_mov_b32_e32 v61, v2
	v_mov_b32_e32 v62, v2
	v_mov_b32_e32 v63, v2
	v_mov_b32_e32 v64, v2
	v_mov_b32_e32 v65, v2
	v_mov_b32_e32 v66, v2
	v_mov_b32_e32 v67, v2
	v_mov_b32_e32 v68, v2
	v_mov_b32_e32 v69, v2
	v_mov_b32_e32 v70, v2
	v_mov_b32_e32 v71, v2
	v_mov_b32_e32 v72, v2
	v_mov_b32_e32 v73, v2
	v_mov_b32_e32 v82, v2
	v_mov_b32_e32 v83, v2
	v_mov_b32_e32 v84, v2
	v_mov_b32_e32 v85, v2
	v_mov_b32_e32 v86, v2
	v_mov_b32_e32 v87, v2
	v_mov_b32_e32 v88, v2
	v_mov_b32_e32 v89, v2
	v_mov_b32_e32 v98, v2
	v_mov_b32_e32 v99, v2
	v_mov_b32_e32 v100, v2
	v_mov_b32_e32 v101, v2
	v_mov_b32_e32 v102, v2
	v_mov_b32_e32 v103, v2
	v_mov_b32_e32 v104, v2
	v_mov_b32_e32 v105, v2
	v_mov_b32_e32 v114, v2
	v_mov_b32_e32 v115, v2
	v_mov_b32_e32 v116, v2
	v_mov_b32_e32 v117, v2
	v_mov_b32_e32 v118, v2
	v_mov_b32_e32 v119, v2
	v_mov_b32_e32 v120, v2
	v_mov_b32_e32 v121, v2
	v_mov_b32_e32 v74, v2
	v_mov_b32_e32 v75, v2
	v_mov_b32_e32 v76, v2
	v_mov_b32_e32 v77, v2
	v_mov_b32_e32 v78, v2
	v_mov_b32_e32 v79, v2
	v_mov_b32_e32 v80, v2
	v_mov_b32_e32 v81, v2
	v_mov_b32_e32 v90, v2
	v_mov_b32_e32 v91, v2
	v_mov_b32_e32 v92, v2
	v_mov_b32_e32 v93, v2
	v_mov_b32_e32 v94, v2
	v_mov_b32_e32 v95, v2
	v_mov_b32_e32 v96, v2
	v_mov_b32_e32 v97, v2
	v_mov_b32_e32 v106, v2
	v_mov_b32_e32 v107, v2
	v_mov_b32_e32 v108, v2
	v_mov_b32_e32 v109, v2
	v_mov_b32_e32 v110, v2
	v_mov_b32_e32 v111, v2
	v_mov_b32_e32 v112, v2
	v_mov_b32_e32 v113, v2
	v_mov_b32_e32 v122, v2
	v_mov_b32_e32 v123, v2
	v_mov_b32_e32 v124, v2
	v_mov_b32_e32 v125, v2
	v_mov_b32_e32 v126, v2
	v_mov_b32_e32 v127, v2
	v_mov_b32_e32 v128, v2
	v_mov_b32_e32 v129, v2
.LBB0_63:
	s_add_i32 vcc_lo, s66, 2
	s_add_u32 s64, s62, 0x100
	s_addc_u32 s65, s63, 0
	s_add_i32 s22, 0, 0x10000
	s_cmp_eq_u32 s59, s66
	s_cselect_b32 s66, s44, s61
	s_cselect_b32 s69, s43, s65
	s_cselect_b32 s68, s42, s64
	s_cselect_b32 s67, s45, s97
	s_add_i32 m0, s52, 0xc000
	ds_read_b128 v[146:149], v189
	ds_read_b128 v[150:153], v189 offset:1024
	ds_read_b128 v[154:157], v189 offset:2048
	ds_read_b128 v[168:171], v189 offset:3072
	ds_read_b128 v[172:175], v189 offset:4096
	ds_read_b128 v[176:179], v189 offset:5120
	ds_read_b128 v[180:183], v189 offset:6144
	ds_read_b128 v[190:193], v189 offset:7168
	global_load_lds_dwordx4 v164, s[62:63]
	s_add_i32 m0, s52, 0xe000
	s_nop 0
	global_load_lds_dwordx4 v166, s[62:63]
	s_waitcnt lgkmcnt(8)
	s_barrier
	s_waitcnt lgkmcnt(0)
	s_setprio 1
	v_mfma_f32_16x16x32_bf16 v[126:129], v[130:133], v[146:149], v[126:129]
	v_mfma_f32_16x16x32_bf16 v[122:125], v[138:141], v[146:149], v[122:125]
	v_mfma_f32_16x16x32_bf16 v[110:113], v[130:133], v[154:157], v[110:113]
	v_mfma_f32_16x16x32_bf16 v[106:109], v[138:141], v[154:157], v[106:109]
	v_mfma_f32_16x16x32_bf16 v[94:97], v[130:133], v[172:175], v[94:97]
	v_mfma_f32_16x16x32_bf16 v[90:93], v[138:141], v[172:175], v[90:93]
	v_mfma_f32_16x16x32_bf16 v[78:81], v[130:133], v[180:183], v[78:81]
	v_mfma_f32_16x16x32_bf16 v[74:77], v[138:141], v[180:183], v[74:77]
	v_mfma_f32_16x16x32_bf16 v[126:129], v[134:137], v[150:153], v[126:129]
	v_mfma_f32_16x16x32_bf16 v[122:125], v[142:145], v[150:153], v[122:125]
	v_mfma_f32_16x16x32_bf16 v[110:113], v[134:137], v[168:171], v[110:113]
	v_mfma_f32_16x16x32_bf16 v[106:109], v[142:145], v[168:171], v[106:109]
	v_mfma_f32_16x16x32_bf16 v[94:97], v[134:137], v[176:179], v[94:97]
	v_mfma_f32_16x16x32_bf16 v[90:93], v[142:145], v[176:179], v[90:93]
	v_mfma_f32_16x16x32_bf16 v[78:81], v[134:137], v[190:193], v[78:81]
	v_mfma_f32_16x16x32_bf16 v[74:77], v[142:145], v[190:193], v[74:77]
	s_setprio 0
	s_barrier
	s_add_i32 s62, 0, 0x14000
	v_add_u32_e32 v184, s62, v188
	s_add_i32 s22, s22, s51
	ds_read_b128 v[202:205], v184
	ds_read_b128 v[206:209], v184 offset:1024
	ds_read_b128 v[210:213], v184 offset:2048
	ds_read_b128 v[214:217], v184 offset:3072
	s_mov_b32 m0, s22
	s_nop 0
	global_load_lds_dwordx4 v0, s[66:67]
	s_add_i32 m0, s22, 0x2000
	s_nop 0
	global_load_lds_dwordx4 v162, s[66:67]
	s_barrier
; #define PG8_STAGE(bufoff, gbase, voff) do { _Pragma("unroll") for (int _i = 0; _i < 2; ++_i) \
;         __builtin_amdgcn_global_load_lds((const unsigned*)((const char*)(gbase) + (voff)[_i]), (LAS unsigned*)(lds + (bufoff) + ldsw + _i * 8192), 16, 0, 0); } while (0)
; #define PG8_LDA(dst, b, h) do { _Pragma("unroll") for (int m = 0; m < 4; ++m) _Pragma("unroll") for (int k = 0; k < 2; ++k) dst[m][k] = *(const LAS bf16x8*)(lds + PG8_SA(b, h) + aoff + m * 2048 + k * 1024); } while (0)
; #define PG8_LDB(dst, b, h) do { _Pragma("unroll") for (int n = 0; n < 2; ++n) _Pragma("unroll") for (int k = 0; k < 2; ++k) dst[n][k] = *(const LAS bf16x8*)(lds + PG8_SB(b, h) + boff + n * 2048 + k * 1024); } while (0)
; #define PG8_MMA(ai, bj, At, Bt) do { __builtin_amdgcn_s_setprio(1); _Pragma("unroll") for (int m = 0; m < 4; ++m) _Pragma("unroll") for (int n = 0; n < 2; ++n) _Pragma("unroll") for (int k = 0; k < 2; ++k) \
;         acc[ai][bj][m][n] = __builtin_amdgcn_mfma_f32_16x16x32_bf16(Bt[n][k], At[m][k], acc[ai][bj][m][n], 0, 0, 0); __builtin_amdgcn_s_setprio(0); } while (0)
; #define PG8_WAIT_V(n) asm volatile("s_waitcnt vmcnt(" #n ")" ::: "memory")
; #define PG8_WAIT_L(n) asm volatile("s_waitcnt lgkmcnt(" #n ")" ::: "memory")
; #define PG8_BAR __builtin_amdgcn_s_barrier()
; #define PG8_SCHED __builtin_amdgcn_sched_barrier(0)
; template <class Epi>
; __device__ __forceinline__ void gemm_phase(LAS unsigned char* lds, const Gemm g, const StaticOrder& S, const Epi& E) {
;     ...
;             PG8_BAR; PG8_WAIT_L(0); PG8_MMA(0, 1, At, B1); PG8_BAR;
;             PG8_LDA(At, 0, 1); PG8_STAGE(PG8_SA(0, 0), a2, voffA);
;             PG8_BAR; PG8_WAIT_L(0); PG8_MMA(1, 0, At, B0); PG8_BAR; PG8_SCHED;
;             PG8_STAGE(PG8_SB(0, 1), b2 + hB, voffB);
;             PG8_WAIT_V(6); PG8_BAR; PG8_MMA(1, 1, At, B1); PG8_BAR;
;             PG8_LDB(B0, 1, 0); PG8_SCHED; PG8_LDA(At, 1, 0); PG8_STAGE(PG8_SA(0, 1), a2 + hA, voffA);
;             PG8_WAIT_L(8); PG8_BAR; PG8_WAIT_L(0); PG8_MMA(0, 0, At, B0); PG8_BAR; PG8_SCHED;
	s_waitcnt lgkmcnt(0)
	s_setprio 1
	v_mfma_f32_16x16x32_bf16 v[118:121], v[202:205], v[146:149], v[118:121]
	v_mfma_f32_16x16x32_bf16 v[114:117], v[210:213], v[146:149], v[114:117]
	v_mfma_f32_16x16x32_bf16 v[102:105], v[202:205], v[154:157], v[102:105]
	v_mfma_f32_16x16x32_bf16 v[98:101], v[210:213], v[154:157], v[98:101]
	v_mfma_f32_16x16x32_bf16 v[86:89], v[202:205], v[172:175], v[86:89]
	v_mfma_f32_16x16x32_bf16 v[82:85], v[210:213], v[172:175], v[82:85]
	v_mfma_f32_16x16x32_bf16 v[70:73], v[202:205], v[180:183], v[70:73]
	v_mfma_f32_16x16x32_bf16 v[66:69], v[210:213], v[180:183], v[66:69]
	v_mfma_f32_16x16x32_bf16 v[118:121], v[206:209], v[150:153], v[118:121]
	v_mfma_f32_16x16x32_bf16 v[114:117], v[214:217], v[150:153], v[114:117]
	v_mfma_f32_16x16x32_bf16 v[102:105], v[206:209], v[168:171], v[102:105]
	v_mfma_f32_16x16x32_bf16 v[98:101], v[214:217], v[168:171], v[98:101]
	v_mfma_f32_16x16x32_bf16 v[86:89], v[206:209], v[176:179], v[86:89]
	v_mfma_f32_16x16x32_bf16 v[82:85], v[214:217], v[176:179], v[82:85]
	v_mfma_f32_16x16x32_bf16 v[70:73], v[206:209], v[190:193], v[70:73]
	v_mfma_f32_16x16x32_bf16 v[66:69], v[214:217], v[190:193], v[66:69]
	s_setprio 0
	s_mov_b32 m0, s52
	s_barrier
	ds_read_b128 v[146:149], v189 offset:16384
	ds_read_b128 v[150:153], v189 offset:17408
	ds_read_b128 v[154:157], v189 offset:18432
	ds_read_b128 v[168:171], v189 offset:19456
	ds_read_b128 v[172:175], v189 offset:20480
	ds_read_b128 v[176:179], v189 offset:21504
	ds_read_b128 v[180:183], v189 offset:22528
	ds_read_b128 v[190:193], v189 offset:23552
	global_load_lds_dwordx4 v158, s[68:69]
	s_mov_b32 m0, s53
	s_nop 0
	global_load_lds_dwordx4 v160, s[68:69]
	s_waitcnt vmcnt(8)
	s_barrier
	s_waitcnt lgkmcnt(0)
	s_setprio 1
	v_mfma_f32_16x16x32_bf16 v[62:65], v[130:133], v[146:149], v[62:65]
	v_mfma_f32_16x16x32_bf16 v[58:61], v[138:141], v[146:149], v[58:61]
	v_mfma_f32_16x16x32_bf16 v[46:49], v[130:133], v[154:157], v[46:49]
	v_mfma_f32_16x16x32_bf16 v[42:45], v[138:141], v[154:157], v[42:45]
	v_mfma_f32_16x16x32_bf16 v[30:33], v[130:133], v[172:175], v[30:33]
	v_mfma_f32_16x16x32_bf16 v[26:29], v[138:141], v[172:175], v[26:29]
	v_mfma_f32_16x16x32_bf16 v[14:17], v[130:133], v[180:183], v[14:17]
	v_mfma_f32_16x16x32_bf16 v[10:13], v[138:141], v[180:183], v[10:13]
	v_mfma_f32_16x16x32_bf16 v[62:65], v[134:137], v[150:153], v[62:65]
	v_mfma_f32_16x16x32_bf16 v[58:61], v[142:145], v[150:153], v[58:61]
	v_mfma_f32_16x16x32_bf16 v[46:49], v[134:137], v[168:171], v[46:49]
	v_mfma_f32_16x16x32_bf16 v[42:45], v[142:145], v[168:171], v[42:45]
	v_mfma_f32_16x16x32_bf16 v[30:33], v[134:137], v[176:179], v[30:33]
	v_mfma_f32_16x16x32_bf16 v[26:29], v[142:145], v[176:179], v[26:29]
	v_mfma_f32_16x16x32_bf16 v[14:17], v[134:137], v[190:193], v[14:17]
	v_mfma_f32_16x16x32_bf16 v[10:13], v[142:145], v[190:193], v[10:13]
	s_setprio 0
	s_barrier
	s_add_u32 s22, s66, 0xb0000
	s_addc_u32 s23, s67, 0
	s_add_i32 s62, s62, s51
	s_mov_b32 m0, s62
	s_nop 0
	global_load_lds_dwordx4 v0, s[22:23]
	s_add_i32 m0, s62, 0x2000
	s_nop 0
	global_load_lds_dwordx4 v162, s[22:23]
	s_waitcnt vmcnt(6)
	s_barrier
	s_setprio 1
	v_mfma_f32_16x16x32_bf16 v[54:57], v[202:205], v[146:149], v[54:57]
	ds_read_b128 v[130:133], v218 offset:32768
	v_mfma_f32_16x16x32_bf16 v[50:53], v[210:213], v[146:149], v[50:53]
	ds_read_b128 v[134:137], v218 offset:33792
	v_mfma_f32_16x16x32_bf16 v[38:41], v[202:205], v[154:157], v[38:41]
	ds_read_b128 v[138:141], v218 offset:34816
	v_mfma_f32_16x16x32_bf16 v[34:37], v[210:213], v[154:157], v[34:37]
	ds_read_b128 v[142:145], v218 offset:35840
	v_mfma_f32_16x16x32_bf16 v[22:25], v[202:205], v[172:175], v[22:25]
	v_mfma_f32_16x16x32_bf16 v[18:21], v[210:213], v[172:175], v[18:21]
	v_mfma_f32_16x16x32_bf16 v[6:9], v[202:205], v[180:183], v[6:9]
	v_mfma_f32_16x16x32_bf16 v[2:5], v[210:213], v[180:183], v[2:5]
	v_mfma_f32_16x16x32_bf16 v[54:57], v[206:209], v[150:153], v[54:57]
	v_mfma_f32_16x16x32_bf16 v[50:53], v[214:217], v[150:153], v[50:53]
	v_mfma_f32_16x16x32_bf16 v[38:41], v[206:209], v[168:171], v[38:41]
	v_mfma_f32_16x16x32_bf16 v[34:37], v[214:217], v[168:171], v[34:37]
	v_mfma_f32_16x16x32_bf16 v[22:25], v[206:209], v[176:179], v[22:25]
	v_mfma_f32_16x16x32_bf16 v[18:21], v[214:217], v[176:179], v[18:21]
	v_mfma_f32_16x16x32_bf16 v[6:9], v[206:209], v[190:193], v[6:9]
	v_mfma_f32_16x16x32_bf16 v[2:5], v[214:217], v[190:193], v[2:5]
	s_setprio 0
	s_add_i32 s62, 0, 0x18000
	s_barrier
	s_add_u32 s22, s68, 0xb0000
	s_addc_u32 s23, s69, 0
	s_mov_b32 m0, s56
	ds_read_b128 v[146:149], v189 offset:32768
	ds_read_b128 v[150:153], v189 offset:33792
	ds_read_b128 v[154:157], v189 offset:34816
	ds_read_b128 v[168:171], v189 offset:35840
	ds_read_b128 v[172:175], v189 offset:36864
	ds_read_b128 v[176:179], v189 offset:37888
	ds_read_b128 v[180:183], v189 offset:38912
	ds_read_b128 v[190:193], v189 offset:39936
	global_load_lds_dwordx4 v158, s[22:23]
	s_mov_b32 m0, s57
	s_nop 0
	global_load_lds_dwordx4 v160, s[22:23]
	s_waitcnt lgkmcnt(8)
	s_barrier
	s_waitcnt lgkmcnt(0)
	s_setprio 1
	v_mfma_f32_16x16x32_bf16 v[126:129], v[130:133], v[146:149], v[126:129]
	v_mfma_f32_16x16x32_bf16 v[122:125], v[138:141], v[146:149], v[122:125]
	v_mfma_f32_16x16x32_bf16 v[110:113], v[130:133], v[154:157], v[110:113]
	v_mfma_f32_16x16x32_bf16 v[106:109], v[138:141], v[154:157], v[106:109]
	v_mfma_f32_16x16x32_bf16 v[94:97], v[130:133], v[172:175], v[94:97]
	v_mfma_f32_16x16x32_bf16 v[90:93], v[138:141], v[172:175], v[90:93]
	v_mfma_f32_16x16x32_bf16 v[78:81], v[130:133], v[180:183], v[78:81]
	v_mfma_f32_16x16x32_bf16 v[74:77], v[138:141], v[180:183], v[74:77]
	v_mfma_f32_16x16x32_bf16 v[126:129], v[134:137], v[150:153], v[126:129]
	v_mfma_f32_16x16x32_bf16 v[122:125], v[142:145], v[150:153], v[122:125]
	v_mfma_f32_16x16x32_bf16 v[110:113], v[134:137], v[168:171], v[110:113]
	v_mfma_f32_16x16x32_bf16 v[106:109], v[142:145], v[168:171], v[106:109]
	v_mfma_f32_16x16x32_bf16 v[94:97], v[134:137], v[176:179], v[94:97]
	v_mfma_f32_16x16x32_bf16 v[90:93], v[142:145], v[176:179], v[90:93]
	v_mfma_f32_16x16x32_bf16 v[78:81], v[134:137], v[190:193], v[78:81]
	v_mfma_f32_16x16x32_bf16 v[74:77], v[142:145], v[190:193], v[74:77]
	s_setprio 0
	s_barrier
; #define PG8_STAGE(bufoff, gbase, voff) do { _Pragma("unroll") for (int _i = 0; _i < 2; ++_i) \
;         __builtin_amdgcn_global_load_lds((const unsigned*)((const char*)(gbase) + (voff)[_i]), (LAS unsigned*)(lds + (bufoff) + ldsw + _i * 8192), 16, 0, 0); } while (0)
; #define PG8_LDA(dst, b, h) do { _Pragma("unroll") for (int m = 0; m < 4; ++m) _Pragma("unroll") for (int k = 0; k < 2; ++k) dst[m][k] = *(const LAS bf16x8*)(lds + PG8_SA(b, h) + aoff + m * 2048 + k * 1024); } while (0)
; #define PG8_LDB(dst, b, h) do { _Pragma("unroll") for (int n = 0; n < 2; ++n) _Pragma("unroll") for (int k = 0; k < 2; ++k) dst[n][k] = *(const LAS bf16x8*)(lds + PG8_SB(b, h) + boff + n * 2048 + k * 1024); } while (0)
; #define PG8_MMA(ai, bj, At, Bt) do { __builtin_amdgcn_s_setprio(1); _Pragma("unroll") for (int m = 0; m < 4; ++m) _Pragma("unroll") for (int n = 0; n < 2; ++n) _Pragma("unroll") for (int k = 0; k < 2; ++k) \
;         acc[ai][bj][m][n] = __builtin_amdgcn_mfma_f32_16x16x32_bf16(Bt[n][k], At[m][k], acc[ai][bj][m][n], 0, 0, 0); __builtin_amdgcn_s_setprio(0); } while (0)
; #define PG8_WAIT_V(n) asm volatile("s_waitcnt vmcnt(" #n ")" ::: "memory")
; #define PG8_WAIT_L(n) asm volatile("s_waitcnt lgkmcnt(" #n ")" ::: "memory")
; #define PG8_BAR __builtin_amdgcn_s_barrier()
; #define PG8_SCHED __builtin_amdgcn_sched_barrier(0)
; template <class Epi>
; __device__ __forceinline__ void gemm_phase(LAS unsigned char* lds, const Gemm g, const StaticOrder& S, const Epi& E) {
;     ...
;             PG8_LDB(B1, 1, 1); PG8_STAGE(PG8_SB(1, 0), b3, voffB);
;             PG8_BAR; PG8_WAIT_L(0); PG8_MMA(0, 1, At, B1); PG8_BAR;
;             PG8_LDA(At, 1, 1); PG8_STAGE(PG8_SA(1, 0), a3, voffA);
;             PG8_BAR; PG8_WAIT_L(0); PG8_MMA(1, 0, At, B0); PG8_BAR; PG8_SCHED;
;             PG8_STAGE(PG8_SB(1, 1), b3 + hB, voffB);
;             PG8_WAIT_V(6); PG8_BAR; PG8_MMA(1, 1, At, B1); PG8_BAR;
	s_add_i32 s63, 0, 0x1c000
	s_add_i32 s22, s62, s51
	v_add_u32_e32 v214, s63, v188
	s_mov_b32 m0, s22
	ds_read_b128 v[202:205], v214
	ds_read_b128 v[206:209], v214 offset:1024
	ds_read_b128 v[210:213], v214 offset:2048
	ds_read_b128 v[214:217], v214 offset:3072
	s_add_u32 s100, s66, 0x80
	s_addc_u32 s101, s67, 0
	global_load_lds_dwordx4 v0, s[100:101]
	s_add_i32 m0, s22, 0x2000
	s_nop 0
	global_load_lds_dwordx4 v162, s[100:101]
	s_barrier
	s_waitcnt lgkmcnt(0)
	s_setprio 1
	v_mfma_f32_16x16x32_bf16 v[118:121], v[202:205], v[146:149], v[118:121]
	v_mfma_f32_16x16x32_bf16 v[114:117], v[210:213], v[146:149], v[114:117]
	v_mfma_f32_16x16x32_bf16 v[102:105], v[202:205], v[154:157], v[102:105]
	v_mfma_f32_16x16x32_bf16 v[98:101], v[210:213], v[154:157], v[98:101]
	v_mfma_f32_16x16x32_bf16 v[86:89], v[202:205], v[172:175], v[86:89]
	v_mfma_f32_16x16x32_bf16 v[82:85], v[210:213], v[172:175], v[82:85]
	v_mfma_f32_16x16x32_bf16 v[70:73], v[202:205], v[180:183], v[70:73]
	v_mfma_f32_16x16x32_bf16 v[66:69], v[210:213], v[180:183], v[66:69]
	v_mfma_f32_16x16x32_bf16 v[118:121], v[206:209], v[150:153], v[118:121]
	v_mfma_f32_16x16x32_bf16 v[114:117], v[214:217], v[150:153], v[114:117]
	v_mfma_f32_16x16x32_bf16 v[102:105], v[206:209], v[168:171], v[102:105]
	v_mfma_f32_16x16x32_bf16 v[98:101], v[214:217], v[168:171], v[98:101]
	v_mfma_f32_16x16x32_bf16 v[86:89], v[206:209], v[176:179], v[86:89]
	v_mfma_f32_16x16x32_bf16 v[82:85], v[214:217], v[176:179], v[82:85]
	v_mfma_f32_16x16x32_bf16 v[70:73], v[206:209], v[190:193], v[70:73]
	v_mfma_f32_16x16x32_bf16 v[66:69], v[214:217], v[190:193], v[66:69]
	s_setprio 0
	s_mov_b32 m0, s54
	s_barrier
	ds_read_b128 v[146:149], v189 offset:49152
	ds_read_b128 v[150:153], v189 offset:50176
	ds_read_b128 v[154:157], v189 offset:51200
	ds_read_b128 v[168:171], v189 offset:52224
	ds_read_b128 v[172:175], v189 offset:53248
	ds_read_b128 v[176:179], v189 offset:54272
	ds_read_b128 v[180:183], v189 offset:55296
	ds_read_b128 v[190:193], v189 offset:56320
	s_add_u32 s100, s68, 0x80
	s_addc_u32 s101, s69, 0
	global_load_lds_dwordx4 v158, s[100:101]
	s_mov_b32 m0, s55
	s_nop 0
	global_load_lds_dwordx4 v160, s[100:101]
	s_waitcnt vmcnt(8)
	s_barrier
	s_waitcnt lgkmcnt(0)
	s_setprio 1
	v_mfma_f32_16x16x32_bf16 v[62:65], v[130:133], v[146:149], v[62:65]
	v_mfma_f32_16x16x32_bf16 v[58:61], v[138:141], v[146:149], v[58:61]
	v_mfma_f32_16x16x32_bf16 v[46:49], v[130:133], v[154:157], v[46:49]
	v_mfma_f32_16x16x32_bf16 v[42:45], v[138:141], v[154:157], v[42:45]
	v_mfma_f32_16x16x32_bf16 v[30:33], v[130:133], v[172:175], v[30:33]
	v_mfma_f32_16x16x32_bf16 v[26:29], v[138:141], v[172:175], v[26:29]
	v_mfma_f32_16x16x32_bf16 v[14:17], v[130:133], v[180:183], v[14:17]
	v_mfma_f32_16x16x32_bf16 v[10:13], v[138:141], v[180:183], v[10:13]
	v_mfma_f32_16x16x32_bf16 v[62:65], v[134:137], v[150:153], v[62:65]
	v_mfma_f32_16x16x32_bf16 v[58:61], v[142:145], v[150:153], v[58:61]
	v_mfma_f32_16x16x32_bf16 v[46:49], v[134:137], v[168:171], v[46:49]
	v_mfma_f32_16x16x32_bf16 v[42:45], v[142:145], v[168:171], v[42:45]
	v_mfma_f32_16x16x32_bf16 v[30:33], v[134:137], v[176:179], v[30:33]
	v_mfma_f32_16x16x32_bf16 v[26:29], v[142:145], v[176:179], v[26:29]
	v_mfma_f32_16x16x32_bf16 v[14:17], v[134:137], v[190:193], v[14:17]
	v_mfma_f32_16x16x32_bf16 v[10:13], v[142:145], v[190:193], v[10:13]
	s_setprio 0
	s_barrier
	s_add_u32 s22, s66, 0xb0080
	s_addc_u32 s23, s67, 0
	s_add_i32 s62, s63, s51
	s_mov_b32 m0, s62
	s_nop 0
	global_load_lds_dwordx4 v0, s[22:23]
	s_add_i32 m0, s62, 0x2000
	s_nop 0
	global_load_lds_dwordx4 v162, s[22:23]
	s_waitcnt vmcnt(6)
	s_barrier
	s_setprio 1
	v_mfma_f32_16x16x32_bf16 v[54:57], v[202:205], v[146:149], v[54:57]
	ds_read_b128 v[130:133], v218
	v_mfma_f32_16x16x32_bf16 v[50:53], v[210:213], v[146:149], v[50:53]
	ds_read_b128 v[134:137], v218 offset:1024
	v_mfma_f32_16x16x32_bf16 v[38:41], v[202:205], v[154:157], v[38:41]
	ds_read_b128 v[138:141], v218 offset:2048
	v_mfma_f32_16x16x32_bf16 v[34:37], v[210:213], v[154:157], v[34:37]
	ds_read_b128 v[142:145], v218 offset:3072
	v_mfma_f32_16x16x32_bf16 v[22:25], v[202:205], v[172:175], v[22:25]
	v_mfma_f32_16x16x32_bf16 v[18:21], v[210:213], v[172:175], v[18:21]
	v_mfma_f32_16x16x32_bf16 v[6:9], v[202:205], v[180:183], v[6:9]
	v_mfma_f32_16x16x32_bf16 v[2:5], v[210:213], v[180:183], v[2:5]
	v_mfma_f32_16x16x32_bf16 v[54:57], v[206:209], v[150:153], v[54:57]
	v_mfma_f32_16x16x32_bf16 v[50:53], v[214:217], v[150:153], v[50:53]
	v_mfma_f32_16x16x32_bf16 v[38:41], v[206:209], v[168:171], v[38:41]
	v_mfma_f32_16x16x32_bf16 v[34:37], v[214:217], v[168:171], v[34:37]
	v_mfma_f32_16x16x32_bf16 v[22:25], v[206:209], v[176:179], v[22:25]
	v_mfma_f32_16x16x32_bf16 v[18:21], v[214:217], v[176:179], v[18:21]
	v_mfma_f32_16x16x32_bf16 v[6:9], v[206:209], v[190:193], v[6:9]
	v_mfma_f32_16x16x32_bf16 v[2:5], v[214:217], v[190:193], v[2:5]
	s_setprio 0
	s_add_u32 s61, s61, 0x100
	s_addc_u32 s97, s97, 0
	s_cmp_ge_i32 vcc_lo, s33
	s_mov_b64 s[62:63], s[64:65]
	s_mov_b32 s66, vcc_lo
	s_barrier
; template <class Epi>
; __device__ __forceinline__ void gemm_phase(LAS unsigned char* lds, const Gemm g, const StaticOrder& S, const Epi& E) {
;     ...
;         }
;         if constexpr (Epi::HAS_PRE) { E(acc, cur, wr, wc, fr, fq, pre); if (has_next) E.pre(pre, nxt, wr, fr); } else E(acc, cur, wr, wc, fr, fq);
;         if (!has_next) break;
;     __device__ __forceinline__ void operator()(const Acc& acc, const Unit& u, int wr, int wc, int fr, int fq) const {
;     ...
;         if (u.split) {
;             float* pt = part + (size_t)(u.split - 1) * 256 * DM;
; #pragma unroll
;             for (int ai = 0; ai < 2; ++ai)
; #pragma unroll
;                 for (int m = 0; m < 4; ++m)
; #pragma unroll
;                     for (int bj = 0; bj < 2; ++bj)
; #pragma unroll
;                         for (int n = 0; n < 2; ++n) *(f32x4*)(pt + (size_t)(wr * 64 + fr + ai * 128 + m * 16) * DM + col0 + bj * 128 + n * 4) = acc[ai][bj][m][n] * sc;
;             return; }
	s_cbranch_scc0 .LBB0_63
	s_waitcnt lgkmcnt(0)
	s_lshl_b32 s22, s46, 8
	v_mov_b32_e32 v133, v186
	v_mov_b32_e32 v132, v187
	s_or_b32 s22, s22, s76
	s_cmp_lg_u32 s60, 0
	v_lshl_add_u32 v168, v132, 3, s22
	v_add_u32_e32 v130, s75, v133
	v_ashrrev_i32_e32 v169, 31, v168
	s_cbranch_scc0 .LBB0_66
	s_ashr_i32 s61, s60, 31
	s_lshl_b64 s[22:23], s[60:61], 20
	s_add_u32 s22, s15, s22
	s_addc_u32 s23, s18, s23
	v_ashrrev_i32_e32 v131, 31, v130
	v_lshl_add_u64 v[134:135], v[168:169], 2, s[22:23]
	v_lshlrev_b64 v[136:137], 12, v[130:131]
	s_mov_b32 s22, 0xfff00000
	v_lshl_add_u64 v[134:135], v[134:135], 0, v[136:137]
	s_mov_b32 s23, -1
	v_lshl_add_u64 v[136:137], v[134:135], 0, s[22:23]
	v_add_co_u32_e32 v138, vcc, s0, v134
	s_mov_b32 s22, 0xfff10000
	s_nop 0
	v_addc_co_u32_e32 v139, vcc, -1, v135, vcc
	s_mov_b32 s23, -1
	global_store_dwordx4 v[138:139], v[126:129], off
	global_store_dwordx4 v[136:137], v[122:125], off offset:16
	global_store_dwordx4 v[136:137], v[118:121], off offset:512
	global_store_dwordx4 v[136:137], v[114:117], off offset:528
	v_lshl_add_u64 v[136:137], v[134:135], 0, s[22:23]
	v_add_co_u32_e32 v138, vcc, s1, v134
	s_mov_b32 s22, 0xfff20000
	s_nop 0
	v_addc_co_u32_e32 v139, vcc, -1, v135, vcc
	s_mov_b32 s23, -1
	global_store_dwordx4 v[138:139], v[110:113], off
	global_store_dwordx4 v[136:137], v[106:109], off offset:16
	global_store_dwordx4 v[136:137], v[102:105], off offset:512
	global_store_dwordx4 v[136:137], v[98:101], off offset:528
	v_lshl_add_u64 v[136:137], v[134:135], 0, s[22:23]
	s_mov_b32 s22, 0xfff20000
	v_add_co_u32_e32 v138, vcc, s22, v134
	s_mov_b32 s22, 0xfff30000
	s_nop 0
	v_addc_co_u32_e32 v139, vcc, -1, v135, vcc
	s_mov_b32 s23, -1
	global_store_dwordx4 v[138:139], v[94:97], off
	global_store_dwordx4 v[136:137], v[90:93], off offset:16
	global_store_dwordx4 v[136:137], v[86:89], off offset:512
	global_store_dwordx4 v[136:137], v[82:85], off offset:528
	v_lshl_add_u64 v[136:137], v[134:135], 0, s[22:23]
	s_mov_b32 s22, 0xfff30000
	v_add_co_u32_e32 v138, vcc, s22, v134
	s_mov_b32 s22, 0xfff80000
	s_nop 0
	v_addc_co_u32_e32 v139, vcc, -1, v135, vcc
	s_mov_b32 s23, -1
	global_store_dwordx4 v[138:139], v[78:81], off
	global_store_dwordx4 v[136:137], v[74:77], off offset:16
	global_store_dwordx4 v[136:137], v[70:73], off offset:512
	global_store_dwordx4 v[136:137], v[66:69], off offset:528
	v_lshl_add_u64 v[136:137], v[134:135], 0, s[22:23]
	s_mov_b32 s22, 0xfff80000
	v_add_co_u32_e32 v138, vcc, s22, v134
	s_mov_b32 s22, 0xfff90000
	s_nop 0
	v_addc_co_u32_e32 v139, vcc, -1, v135, vcc
	s_mov_b32 s23, -1
	global_store_dwordx4 v[138:139], v[62:65], off
	global_store_dwordx4 v[136:137], v[58:61], off offset:16
	global_store_dwordx4 v[136:137], v[54:57], off offset:512
	global_store_dwordx4 v[136:137], v[50:53], off offset:528
	v_lshl_add_u64 v[136:137], v[134:135], 0, s[22:23]
	s_mov_b32 s22, 0xfff90000
	v_add_co_u32_e32 v138, vcc, s22, v134
	s_mov_b32 s22, 0xfffa0000
	s_nop 0
	v_addc_co_u32_e32 v139, vcc, -1, v135, vcc
	s_mov_b32 s23, -1
	global_store_dwordx4 v[138:139], v[46:49], off
	global_store_dwordx4 v[136:137], v[42:45], off offset:16
	global_store_dwordx4 v[136:137], v[38:41], off offset:512
	global_store_dwordx4 v[136:137], v[34:37], off offset:528
	v_lshl_add_u64 v[136:137], v[134:135], 0, s[22:23]
	s_mov_b32 s22, 0xfffa0000
	v_add_co_u32_e32 v138, vcc, s22, v134
	s_mov_b32 s22, 0xfffb0000
	s_nop 0
	v_addc_co_u32_e32 v139, vcc, -1, v135, vcc
	s_mov_b32 s23, -1
	global_store_dwordx4 v[138:139], v[30:33], off
	global_store_dwordx4 v[136:137], v[26:29], off offset:16
	global_store_dwordx4 v[136:137], v[22:25], off offset:512
	global_store_dwordx4 v[136:137], v[18:21], off offset:528
	v_lshl_add_u64 v[136:137], v[134:135], 0, s[22:23]
	v_add_co_u32_e32 v134, vcc, 0xfffb0000, v134
	s_nop 1
	v_addc_co_u32_e32 v135, vcc, -1, v135, vcc
	global_store_dwordx4 v[134:135], v[14:17], off
	global_store_dwordx4 v[136:137], v[10:13], off offset:16
	global_store_dwordx4 v[136:137], v[6:9], off offset:512
	global_store_dwordx4 v[136:137], v[2:5], off offset:528
	s_cbranch_execnz .LBB0_47
	s_branch .LBB0_67

; template <class Epi>
; __device__ __forceinline__ void gemm_phase(LAS unsigned char* lds, const Gemm g, const StaticOrder& S, const Epi& E) {
;     ...
;         const bool has_next = S.next(ui + 1, nxt);
;         const char* nA = has_next ? (const char*)(nxt.alt ? g.A2 : g.A) + (size_t)nxt.pm * tA + (size_t)nxt.k0 * 2 : cA; const char* nB = has_next ? (const char*)(nxt.alt ? g.Bt2 : g.Bt) + (size_t)nxt.pn * tB + (size_t)nxt.k0 * 2 : cB;
;     ...
;         if (!(Epi::PAIRS && cur.alt == 0)) {
; #pragma unroll
;         for (int a = 0; a < 2; ++a)
; #pragma unroll
;             for (int b = 0; b < 2; ++b)
; #pragma unroll
;                 for (int m = 0; m < 4; ++m)
; #pragma unroll
;                     for (int n = 0; n < 2; ++n) acc[a][b][m][n] = (f32x4){0.f, 0.f, 0.f, 0.f}; }
;         cur = nxt; cA = nA; cB = nB; ++ui;
.LBB0_208:
	v_mov_b64_e32 v[2:3], 0x210
	s_ashr_i32 s59, s58, 31
	v_cmp_lt_i64_e32 vcc, s[60:61], v[2:3]
	s_lshl_b64 s[60:61], s[58:59], 19
	s_add_u32 s22, s6, s60
	s_addc_u32 s23, s7, s61
	s_ashr_i32 s45, s44, 31
	s_lshl_b64 s[62:63], s[44:45], 1
	s_add_u32 s60, s22, s62
	s_addc_u32 s61, s23, s63
	s_and_b64 s[74:75], vcc, exec
	s_cselect_b32 s33, s61, s69
	s_cselect_b32 s45, s60, s68
	s_ashr_i32 s57, s56, 31
	s_lshl_b64 s[74:75], s[56:57], 19
	s_add_u32 s22, s15, s74
	s_addc_u32 s23, s18, s75
	s_add_u32 s62, s22, s62
	s_addc_u32 s63, s23, s63
	s_and_b64 s[74:75], vcc, exec
	s_cselect_b32 s57, s63, s71
	s_cselect_b32 s59, s62, s70
	s_add_i32 s65, s30, -2
	s_add_u32 s68, s68, 0x40080
	s_addc_u32 s69, s69, 0
	s_add_u32 s67, s70, 0x100
	v_mov_b32_e32 v2, 0
	s_addc_u32 s97, s71, 0
	s_mov_b32 s70, 0
	v_mov_b32_e32 v3, v2
	v_mov_b32_e32 v4, v2
	v_mov_b32_e32 v5, v2
	v_mov_b32_e32 v6, v2
	v_mov_b32_e32 v7, v2
	v_mov_b32_e32 v8, v2
	v_mov_b32_e32 v9, v2
	v_mov_b32_e32 v18, v2
	v_mov_b32_e32 v19, v2
	v_mov_b32_e32 v20, v2
	v_mov_b32_e32 v21, v2
	v_mov_b32_e32 v22, v2
	v_mov_b32_e32 v23, v2
	v_mov_b32_e32 v24, v2
	v_mov_b32_e32 v25, v2
	v_mov_b32_e32 v34, v2
	v_mov_b32_e32 v35, v2
	v_mov_b32_e32 v36, v2
	v_mov_b32_e32 v37, v2
	v_mov_b32_e32 v38, v2
	v_mov_b32_e32 v39, v2
	v_mov_b32_e32 v40, v2
	v_mov_b32_e32 v41, v2
	v_mov_b32_e32 v50, v2
	v_mov_b32_e32 v51, v2
	v_mov_b32_e32 v52, v2
	v_mov_b32_e32 v53, v2
	v_mov_b32_e32 v54, v2
	v_mov_b32_e32 v55, v2
	v_mov_b32_e32 v56, v2
	v_mov_b32_e32 v57, v2
	v_mov_b32_e32 v10, v2
	v_mov_b32_e32 v11, v2
	v_mov_b32_e32 v12, v2
	v_mov_b32_e32 v13, v2
	v_mov_b32_e32 v14, v2
	v_mov_b32_e32 v15, v2
	v_mov_b32_e32 v16, v2
	v_mov_b32_e32 v17, v2
	v_mov_b32_e32 v26, v2
	v_mov_b32_e32 v27, v2
	v_mov_b32_e32 v28, v2
	v_mov_b32_e32 v29, v2
	v_mov_b32_e32 v30, v2
	v_mov_b32_e32 v31, v2
	v_mov_b32_e32 v32, v2
	v_mov_b32_e32 v33, v2
	v_mov_b32_e32 v42, v2
	v_mov_b32_e32 v43, v2
	v_mov_b32_e32 v44, v2
	v_mov_b32_e32 v45, v2
	v_mov_b32_e32 v46, v2
	v_mov_b32_e32 v47, v2
	v_mov_b32_e32 v48, v2
	v_mov_b32_e32 v49, v2
	v_mov_b32_e32 v58, v2
	v_mov_b32_e32 v59, v2
	v_mov_b32_e32 v60, v2
	v_mov_b32_e32 v61, v2
	v_mov_b32_e32 v62, v2
	v_mov_b32_e32 v63, v2
	v_mov_b32_e32 v64, v2
	v_mov_b32_e32 v65, v2
	v_mov_b32_e32 v66, v2
	v_mov_b32_e32 v67, v2
	v_mov_b32_e32 v68, v2
	v_mov_b32_e32 v69, v2
	v_mov_b32_e32 v70, v2
	v_mov_b32_e32 v71, v2
	v_mov_b32_e32 v72, v2
	v_mov_b32_e32 v73, v2
	v_mov_b32_e32 v82, v2
	v_mov_b32_e32 v83, v2
	v_mov_b32_e32 v84, v2
	v_mov_b32_e32 v85, v2
	v_mov_b32_e32 v86, v2
	v_mov_b32_e32 v87, v2
	v_mov_b32_e32 v88, v2
	v_mov_b32_e32 v89, v2
	v_mov_b32_e32 v98, v2
	v_mov_b32_e32 v99, v2
	v_mov_b32_e32 v100, v2
	v_mov_b32_e32 v101, v2
	v_mov_b32_e32 v102, v2
	v_mov_b32_e32 v103, v2
	v_mov_b32_e32 v104, v2
	v_mov_b32_e32 v105, v2
	v_mov_b32_e32 v114, v2
	v_mov_b32_e32 v115, v2
	v_mov_b32_e32 v116, v2
	v_mov_b32_e32 v117, v2
	v_mov_b32_e32 v118, v2
	v_mov_b32_e32 v119, v2
	v_mov_b32_e32 v120, v2
	v_mov_b32_e32 v121, v2
	v_mov_b32_e32 v74, v2
	v_mov_b32_e32 v75, v2
	v_mov_b32_e32 v76, v2
	v_mov_b32_e32 v77, v2
	v_mov_b32_e32 v78, v2
	v_mov_b32_e32 v79, v2
	v_mov_b32_e32 v80, v2
	v_mov_b32_e32 v81, v2
	v_mov_b32_e32 v90, v2
	v_mov_b32_e32 v91, v2
	v_mov_b32_e32 v92, v2
	v_mov_b32_e32 v93, v2
	v_mov_b32_e32 v94, v2
	v_mov_b32_e32 v95, v2
	v_mov_b32_e32 v96, v2
	v_mov_b32_e32 v97, v2
	v_mov_b32_e32 v106, v2
	v_mov_b32_e32 v107, v2
	v_mov_b32_e32 v108, v2
	v_mov_b32_e32 v109, v2
	v_mov_b32_e32 v110, v2
	v_mov_b32_e32 v111, v2
	v_mov_b32_e32 v112, v2
	v_mov_b32_e32 v113, v2
	v_mov_b32_e32 v122, v2
	v_mov_b32_e32 v123, v2
	v_mov_b32_e32 v124, v2
	v_mov_b32_e32 v125, v2
	v_mov_b32_e32 v126, v2
	v_mov_b32_e32 v127, v2
	v_mov_b32_e32 v128, v2
	v_mov_b32_e32 v129, v2
	s_waitcnt vmcnt(0)
	v_add_u32_e32 v218, 0x10000, v188
	ds_read_b128 v[130:133], v218
	ds_read_b128 v[134:137], v218 offset:1024
	ds_read_b128 v[138:141], v218 offset:2048
	ds_read_b128 v[142:145], v218 offset:3072
.LBB0_209:
	s_add_i32 vcc_lo, s70, 2
	s_add_u32 s22, s68, 0xfffc0080
	s_addc_u32 s23, s69, -1
	s_add_i32 vcc_hi, 0, 0x10000
	s_cmp_eq_u32 s65, s70
	s_cselect_b32 s70, s59, s67
	s_cselect_b32 s75, s33, s23
	s_cselect_b32 s74, s45, s22
	s_cselect_b32 s71, s57, s97
	s_add_i32 m0, s43, 0xc000
	ds_read_b128 v[146:149], v189
	ds_read_b128 v[150:153], v189 offset:1024
	ds_read_b128 v[154:157], v189 offset:2048
	ds_read_b128 v[168:171], v189 offset:3072
	ds_read_b128 v[172:175], v189 offset:4096
	ds_read_b128 v[176:179], v189 offset:5120
	ds_read_b128 v[180:183], v189 offset:6144
	ds_read_b128 v[190:193], v189 offset:7168
	global_load_lds_dwordx4 v164, s[68:69]
	s_add_i32 m0, s43, 0xe000
	s_nop 0
	global_load_lds_dwordx4 v166, s[68:69]
	s_waitcnt lgkmcnt(8)
	s_barrier
	s_waitcnt lgkmcnt(0)
	s_setprio 1
	v_mfma_f32_16x16x32_bf16 v[126:129], v[130:133], v[146:149], v[126:129]
	v_mfma_f32_16x16x32_bf16 v[122:125], v[138:141], v[146:149], v[122:125]
	v_mfma_f32_16x16x32_bf16 v[110:113], v[130:133], v[154:157], v[110:113]
	v_mfma_f32_16x16x32_bf16 v[106:109], v[138:141], v[154:157], v[106:109]
	v_mfma_f32_16x16x32_bf16 v[94:97], v[130:133], v[172:175], v[94:97]
	v_mfma_f32_16x16x32_bf16 v[90:93], v[138:141], v[172:175], v[90:93]
	v_mfma_f32_16x16x32_bf16 v[78:81], v[130:133], v[180:183], v[78:81]
	v_mfma_f32_16x16x32_bf16 v[74:77], v[138:141], v[180:183], v[74:77]
	v_mfma_f32_16x16x32_bf16 v[126:129], v[134:137], v[150:153], v[126:129]
	v_mfma_f32_16x16x32_bf16 v[122:125], v[142:145], v[150:153], v[122:125]
	v_mfma_f32_16x16x32_bf16 v[110:113], v[134:137], v[168:171], v[110:113]
	v_mfma_f32_16x16x32_bf16 v[106:109], v[142:145], v[168:171], v[106:109]
	v_mfma_f32_16x16x32_bf16 v[94:97], v[134:137], v[176:179], v[94:97]
	v_mfma_f32_16x16x32_bf16 v[90:93], v[142:145], v[176:179], v[90:93]
	v_mfma_f32_16x16x32_bf16 v[78:81], v[134:137], v[190:193], v[78:81]
	v_mfma_f32_16x16x32_bf16 v[74:77], v[142:145], v[190:193], v[74:77]
	s_setprio 0
	s_barrier
; #define PG8_STAGE(bufoff, gbase, voff) do { _Pragma("unroll") for (int _i = 0; _i < 2; ++_i) \
;         __builtin_amdgcn_global_load_lds((const unsigned*)((const char*)(gbase) + (voff)[_i]), (LAS unsigned*)(lds + (bufoff) + ldsw + _i * 8192), 16, 0, 0); } while (0)
; #define PG8_LDA(dst, b, h) do { _Pragma("unroll") for (int m = 0; m < 4; ++m) _Pragma("unroll") for (int k = 0; k < 2; ++k) dst[m][k] = *(const LAS bf16x8*)(lds + PG8_SA(b, h) + aoff + m * 2048 + k * 1024); } while (0)
; #define PG8_LDB(dst, b, h) do { _Pragma("unroll") for (int n = 0; n < 2; ++n) _Pragma("unroll") for (int k = 0; k < 2; ++k) dst[n][k] = *(const LAS bf16x8*)(lds + PG8_SB(b, h) + boff + n * 2048 + k * 1024); } while (0)
; #define PG8_MMA(ai, bj, At, Bt) do { __builtin_amdgcn_s_setprio(1); _Pragma("unroll") for (int m = 0; m < 4; ++m) _Pragma("unroll") for (int n = 0; n < 2; ++n) _Pragma("unroll") for (int k = 0; k < 2; ++k) \
;         acc[ai][bj][m][n] = __builtin_amdgcn_mfma_f32_16x16x32_bf16(Bt[n][k], At[m][k], acc[ai][bj][m][n], 0, 0, 0); __builtin_amdgcn_s_setprio(0); } while (0)
; #define PG8_WAIT_V(n) asm volatile("s_waitcnt vmcnt(" #n ")" ::: "memory")
; #define PG8_WAIT_L(n) asm volatile("s_waitcnt lgkmcnt(" #n ")" ::: "memory")
; #define PG8_BAR __builtin_amdgcn_s_barrier()
; #define PG8_SCHED __builtin_amdgcn_sched_barrier(0)
; template <class Epi>
; __device__ __forceinline__ void gemm_phase(LAS unsigned char* lds, const Gemm g, const StaticOrder& S, const Epi& E) {
;     ...
;             PG8_WAIT_L(8); PG8_BAR; PG8_WAIT_L(0); PG8_MMA(0, 0, At, B0); PG8_BAR; PG8_SCHED;
;             PG8_LDB(B1, 0, 1); PG8_STAGE(PG8_SB(0, 0), b2, voffB);
;             PG8_BAR; PG8_WAIT_L(0); PG8_MMA(0, 1, At, B1); PG8_BAR;
;             PG8_LDA(At, 0, 1); PG8_STAGE(PG8_SA(0, 0), a2, voffA);
;             PG8_BAR; PG8_WAIT_L(0); PG8_MMA(1, 0, At, B0); PG8_BAR; PG8_SCHED;
;             PG8_STAGE(PG8_SB(0, 1), b2 + hB, voffB);
;             PG8_WAIT_V(6); PG8_BAR; PG8_MMA(1, 1, At, B1); PG8_BAR;
;             PG8_LDB(B0, 1, 0); PG8_SCHED; PG8_LDA(At, 1, 0); PG8_STAGE(PG8_SA(0, 1), a2 + hA, voffA);
	s_add_i32 s77, 0, 0x14000
	v_add_u32_e32 v184, s77, v188
	s_add_i32 s22, vcc_hi, s50
	ds_read_b128 v[202:205], v184
	ds_read_b128 v[206:209], v184 offset:1024
	ds_read_b128 v[210:213], v184 offset:2048
	ds_read_b128 v[214:217], v184 offset:3072
	s_mov_b32 m0, s22
	s_nop 0
	global_load_lds_dwordx4 v0, s[70:71]
	s_add_i32 m0, s22, 0x2000
	s_nop 0
	global_load_lds_dwordx4 v162, s[70:71]
	s_barrier
	s_waitcnt lgkmcnt(0)
	s_setprio 1
	v_mfma_f32_16x16x32_bf16 v[118:121], v[202:205], v[146:149], v[118:121]
	v_mfma_f32_16x16x32_bf16 v[114:117], v[210:213], v[146:149], v[114:117]
	v_mfma_f32_16x16x32_bf16 v[102:105], v[202:205], v[154:157], v[102:105]
	v_mfma_f32_16x16x32_bf16 v[98:101], v[210:213], v[154:157], v[98:101]
	v_mfma_f32_16x16x32_bf16 v[86:89], v[202:205], v[172:175], v[86:89]
	v_mfma_f32_16x16x32_bf16 v[82:85], v[210:213], v[172:175], v[82:85]
	v_mfma_f32_16x16x32_bf16 v[70:73], v[202:205], v[180:183], v[70:73]
	v_mfma_f32_16x16x32_bf16 v[66:69], v[210:213], v[180:183], v[66:69]
	v_mfma_f32_16x16x32_bf16 v[118:121], v[206:209], v[150:153], v[118:121]
	v_mfma_f32_16x16x32_bf16 v[114:117], v[214:217], v[150:153], v[114:117]
	v_mfma_f32_16x16x32_bf16 v[102:105], v[206:209], v[168:171], v[102:105]
	v_mfma_f32_16x16x32_bf16 v[98:101], v[214:217], v[168:171], v[98:101]
	v_mfma_f32_16x16x32_bf16 v[86:89], v[206:209], v[176:179], v[86:89]
	v_mfma_f32_16x16x32_bf16 v[82:85], v[214:217], v[176:179], v[82:85]
	v_mfma_f32_16x16x32_bf16 v[70:73], v[206:209], v[190:193], v[70:73]
	v_mfma_f32_16x16x32_bf16 v[66:69], v[214:217], v[190:193], v[66:69]
	s_setprio 0
	s_mov_b32 m0, s43
	s_barrier
	ds_read_b128 v[146:149], v189 offset:16384
	ds_read_b128 v[150:153], v189 offset:17408
	ds_read_b128 v[154:157], v189 offset:18432
	ds_read_b128 v[168:171], v189 offset:19456
	ds_read_b128 v[172:175], v189 offset:20480
	ds_read_b128 v[176:179], v189 offset:21504
	ds_read_b128 v[180:183], v189 offset:22528
	ds_read_b128 v[190:193], v189 offset:23552
	global_load_lds_dwordx4 v158, s[74:75]
	s_mov_b32 m0, s51
	s_nop 0
	global_load_lds_dwordx4 v160, s[74:75]
	s_waitcnt vmcnt(8)
	s_barrier
	s_waitcnt lgkmcnt(0)
	s_setprio 1
	v_mfma_f32_16x16x32_bf16 v[62:65], v[130:133], v[146:149], v[62:65]
	v_mfma_f32_16x16x32_bf16 v[58:61], v[138:141], v[146:149], v[58:61]
	v_mfma_f32_16x16x32_bf16 v[46:49], v[130:133], v[154:157], v[46:49]
	v_mfma_f32_16x16x32_bf16 v[42:45], v[138:141], v[154:157], v[42:45]
	v_mfma_f32_16x16x32_bf16 v[30:33], v[130:133], v[172:175], v[30:33]
	v_mfma_f32_16x16x32_bf16 v[26:29], v[138:141], v[172:175], v[26:29]
	v_mfma_f32_16x16x32_bf16 v[14:17], v[130:133], v[180:183], v[14:17]
	v_mfma_f32_16x16x32_bf16 v[10:13], v[138:141], v[180:183], v[10:13]
	v_mfma_f32_16x16x32_bf16 v[62:65], v[134:137], v[150:153], v[62:65]
	v_mfma_f32_16x16x32_bf16 v[58:61], v[142:145], v[150:153], v[58:61]
	v_mfma_f32_16x16x32_bf16 v[46:49], v[134:137], v[168:171], v[46:49]
	v_mfma_f32_16x16x32_bf16 v[42:45], v[142:145], v[168:171], v[42:45]
	v_mfma_f32_16x16x32_bf16 v[30:33], v[134:137], v[176:179], v[30:33]
	v_mfma_f32_16x16x32_bf16 v[26:29], v[142:145], v[176:179], v[26:29]
	v_mfma_f32_16x16x32_bf16 v[14:17], v[134:137], v[190:193], v[14:17]
	v_mfma_f32_16x16x32_bf16 v[10:13], v[142:145], v[190:193], v[10:13]
	s_setprio 0
	s_barrier
	s_add_u32 s22, s70, 0x40000
	s_addc_u32 s23, s71, 0
	s_add_i32 s77, s77, s50
	s_mov_b32 m0, s77
	s_nop 0
	global_load_lds_dwordx4 v0, s[22:23]
	s_add_i32 m0, s77, 0x2000
	s_nop 0
	global_load_lds_dwordx4 v162, s[22:23]
	s_waitcnt vmcnt(6)
	s_barrier
	s_setprio 1
	v_mfma_f32_16x16x32_bf16 v[54:57], v[202:205], v[146:149], v[54:57]
	ds_read_b128 v[130:133], v218 offset:32768
	v_mfma_f32_16x16x32_bf16 v[50:53], v[210:213], v[146:149], v[50:53]
	ds_read_b128 v[134:137], v218 offset:33792
	v_mfma_f32_16x16x32_bf16 v[38:41], v[202:205], v[154:157], v[38:41]
	ds_read_b128 v[138:141], v218 offset:34816
	v_mfma_f32_16x16x32_bf16 v[34:37], v[210:213], v[154:157], v[34:37]
	ds_read_b128 v[142:145], v218 offset:35840
	v_mfma_f32_16x16x32_bf16 v[22:25], v[202:205], v[172:175], v[22:25]
	v_mfma_f32_16x16x32_bf16 v[18:21], v[210:213], v[172:175], v[18:21]
	v_mfma_f32_16x16x32_bf16 v[6:9], v[202:205], v[180:183], v[6:9]
	v_mfma_f32_16x16x32_bf16 v[2:5], v[210:213], v[180:183], v[2:5]
	v_mfma_f32_16x16x32_bf16 v[54:57], v[206:209], v[150:153], v[54:57]
	v_mfma_f32_16x16x32_bf16 v[50:53], v[214:217], v[150:153], v[50:53]
	v_mfma_f32_16x16x32_bf16 v[38:41], v[206:209], v[168:171], v[38:41]
	v_mfma_f32_16x16x32_bf16 v[34:37], v[214:217], v[168:171], v[34:37]
	v_mfma_f32_16x16x32_bf16 v[22:25], v[206:209], v[176:179], v[22:25]
	v_mfma_f32_16x16x32_bf16 v[18:21], v[214:217], v[176:179], v[18:21]
	v_mfma_f32_16x16x32_bf16 v[6:9], v[206:209], v[190:193], v[6:9]
	v_mfma_f32_16x16x32_bf16 v[2:5], v[214:217], v[190:193], v[2:5]
	s_setprio 0
	s_add_i32 s77, 0, 0x18000
	s_barrier
	s_add_u32 s22, s74, 0x40000
	s_addc_u32 s23, s75, 0
	s_mov_b32 m0, s52
	ds_read_b128 v[146:149], v189 offset:32768
	ds_read_b128 v[150:153], v189 offset:33792
	ds_read_b128 v[154:157], v189 offset:34816
	ds_read_b128 v[168:171], v189 offset:35840
	ds_read_b128 v[172:175], v189 offset:36864
	ds_read_b128 v[176:179], v189 offset:37888
	ds_read_b128 v[180:183], v189 offset:38912
	ds_read_b128 v[190:193], v189 offset:39936
	global_load_lds_dwordx4 v158, s[22:23]
	s_mov_b32 m0, s53
	s_nop 0
	global_load_lds_dwordx4 v160, s[22:23]
	s_waitcnt lgkmcnt(8)
	s_barrier
; #define PG8_STAGE(bufoff, gbase, voff) do { _Pragma("unroll") for (int _i = 0; _i < 2; ++_i) \
;         __builtin_amdgcn_global_load_lds((const unsigned*)((const char*)(gbase) + (voff)[_i]), (LAS unsigned*)(lds + (bufoff) + ldsw + _i * 8192), 16, 0, 0); } while (0)
; #define PG8_LDA(dst, b, h) do { _Pragma("unroll") for (int m = 0; m < 4; ++m) _Pragma("unroll") for (int k = 0; k < 2; ++k) dst[m][k] = *(const LAS bf16x8*)(lds + PG8_SA(b, h) + aoff + m * 2048 + k * 1024); } while (0)
; #define PG8_LDB(dst, b, h) do { _Pragma("unroll") for (int n = 0; n < 2; ++n) _Pragma("unroll") for (int k = 0; k < 2; ++k) dst[n][k] = *(const LAS bf16x8*)(lds + PG8_SB(b, h) + boff + n * 2048 + k * 1024); } while (0)
; #define PG8_MMA(ai, bj, At, Bt) do { __builtin_amdgcn_s_setprio(1); _Pragma("unroll") for (int m = 0; m < 4; ++m) _Pragma("unroll") for (int n = 0; n < 2; ++n) _Pragma("unroll") for (int k = 0; k < 2; ++k) \
;         acc[ai][bj][m][n] = __builtin_amdgcn_mfma_f32_16x16x32_bf16(Bt[n][k], At[m][k], acc[ai][bj][m][n], 0, 0, 0); __builtin_amdgcn_s_setprio(0); } while (0)
; #define PG8_WAIT_V(n) asm volatile("s_waitcnt vmcnt(" #n ")" ::: "memory")
; #define PG8_WAIT_L(n) asm volatile("s_waitcnt lgkmcnt(" #n ")" ::: "memory")
; #define PG8_BAR __builtin_amdgcn_s_barrier()
; #define PG8_SCHED __builtin_amdgcn_sched_barrier(0)
; template <class Epi>
; __device__ __forceinline__ void gemm_phase(LAS unsigned char* lds, const Gemm g, const StaticOrder& S, const Epi& E) {
;     ...
;             PG8_LDB(B0, 1, 0); PG8_SCHED; PG8_LDA(At, 1, 0); PG8_STAGE(PG8_SA(0, 1), a2 + hA, voffA);
;             PG8_WAIT_L(8); PG8_BAR; PG8_WAIT_L(0); PG8_MMA(0, 0, At, B0); PG8_BAR; PG8_SCHED;
;             PG8_LDB(B1, 1, 1); PG8_STAGE(PG8_SB(1, 0), b3, voffB);
;             PG8_BAR; PG8_WAIT_L(0); PG8_MMA(0, 1, At, B1); PG8_BAR;
;             PG8_LDA(At, 1, 1); PG8_STAGE(PG8_SA(1, 0), a3, voffA);
;             PG8_BAR; PG8_WAIT_L(0); PG8_MMA(1, 0, At, B0); PG8_BAR; PG8_SCHED;
;             PG8_STAGE(PG8_SB(1, 1), b3 + hB, voffB);
;             PG8_WAIT_V(6); PG8_BAR; PG8_MMA(1, 1, At, B1); PG8_BAR;
	s_waitcnt lgkmcnt(0)
	s_setprio 1
	v_mfma_f32_16x16x32_bf16 v[126:129], v[130:133], v[146:149], v[126:129]
	v_mfma_f32_16x16x32_bf16 v[122:125], v[138:141], v[146:149], v[122:125]
	v_mfma_f32_16x16x32_bf16 v[110:113], v[130:133], v[154:157], v[110:113]
	v_mfma_f32_16x16x32_bf16 v[106:109], v[138:141], v[154:157], v[106:109]
	v_mfma_f32_16x16x32_bf16 v[94:97], v[130:133], v[172:175], v[94:97]
	v_mfma_f32_16x16x32_bf16 v[90:93], v[138:141], v[172:175], v[90:93]
	v_mfma_f32_16x16x32_bf16 v[78:81], v[130:133], v[180:183], v[78:81]
	v_mfma_f32_16x16x32_bf16 v[74:77], v[138:141], v[180:183], v[74:77]
	v_mfma_f32_16x16x32_bf16 v[126:129], v[134:137], v[150:153], v[126:129]
	v_mfma_f32_16x16x32_bf16 v[122:125], v[142:145], v[150:153], v[122:125]
	v_mfma_f32_16x16x32_bf16 v[110:113], v[134:137], v[168:171], v[110:113]
	v_mfma_f32_16x16x32_bf16 v[106:109], v[142:145], v[168:171], v[106:109]
	v_mfma_f32_16x16x32_bf16 v[94:97], v[134:137], v[176:179], v[94:97]
	v_mfma_f32_16x16x32_bf16 v[90:93], v[142:145], v[176:179], v[90:93]
	v_mfma_f32_16x16x32_bf16 v[78:81], v[134:137], v[190:193], v[78:81]
	v_mfma_f32_16x16x32_bf16 v[74:77], v[142:145], v[190:193], v[74:77]
	s_setprio 0
	s_barrier
	s_add_i32 s22, s77, s50
	v_add_u32_e32 v214, 0x1c000, v188
	s_mov_b32 m0, s22
	ds_read_b128 v[202:205], v214
	ds_read_b128 v[206:209], v214 offset:1024
	ds_read_b128 v[210:213], v214 offset:2048
	ds_read_b128 v[214:217], v214 offset:3072
	s_add_u32 s100, s70, 0x80
	s_addc_u32 s101, s71, 0
	global_load_lds_dwordx4 v0, s[100:101]
	s_add_i32 m0, s22, 0x2000
	s_nop 0
	global_load_lds_dwordx4 v162, s[100:101]
	s_barrier
	s_waitcnt lgkmcnt(0)
	s_setprio 1
	v_mfma_f32_16x16x32_bf16 v[118:121], v[202:205], v[146:149], v[118:121]
	v_mfma_f32_16x16x32_bf16 v[114:117], v[210:213], v[146:149], v[114:117]
	v_mfma_f32_16x16x32_bf16 v[102:105], v[202:205], v[154:157], v[102:105]
	v_mfma_f32_16x16x32_bf16 v[98:101], v[210:213], v[154:157], v[98:101]
	v_mfma_f32_16x16x32_bf16 v[86:89], v[202:205], v[172:175], v[86:89]
	v_mfma_f32_16x16x32_bf16 v[82:85], v[210:213], v[172:175], v[82:85]
	v_mfma_f32_16x16x32_bf16 v[70:73], v[202:205], v[180:183], v[70:73]
	v_mfma_f32_16x16x32_bf16 v[66:69], v[210:213], v[180:183], v[66:69]
	v_mfma_f32_16x16x32_bf16 v[118:121], v[206:209], v[150:153], v[118:121]
	v_mfma_f32_16x16x32_bf16 v[114:117], v[214:217], v[150:153], v[114:117]
	v_mfma_f32_16x16x32_bf16 v[102:105], v[206:209], v[168:171], v[102:105]
	v_mfma_f32_16x16x32_bf16 v[98:101], v[214:217], v[168:171], v[98:101]
	v_mfma_f32_16x16x32_bf16 v[86:89], v[206:209], v[176:179], v[86:89]
	v_mfma_f32_16x16x32_bf16 v[82:85], v[214:217], v[176:179], v[82:85]
	v_mfma_f32_16x16x32_bf16 v[70:73], v[206:209], v[190:193], v[70:73]
	v_mfma_f32_16x16x32_bf16 v[66:69], v[214:217], v[190:193], v[66:69]
	s_setprio 0
	s_mov_b32 m0, s55
	s_barrier
	ds_read_b128 v[146:149], v189 offset:49152
	ds_read_b128 v[150:153], v189 offset:50176
	ds_read_b128 v[154:157], v189 offset:51200
	ds_read_b128 v[168:171], v189 offset:52224
	ds_read_b128 v[172:175], v189 offset:53248
	ds_read_b128 v[176:179], v189 offset:54272
	ds_read_b128 v[180:183], v189 offset:55296
	ds_read_b128 v[190:193], v189 offset:56320
	s_add_u32 s100, s74, 0x80
	s_addc_u32 s101, s75, 0
	global_load_lds_dwordx4 v158, s[100:101]
	s_mov_b32 m0, s48
	s_nop 0
	global_load_lds_dwordx4 v160, s[100:101]
	s_waitcnt vmcnt(8)
	s_barrier
	s_waitcnt lgkmcnt(0)
	s_setprio 1
	v_mfma_f32_16x16x32_bf16 v[62:65], v[130:133], v[146:149], v[62:65]
	v_mfma_f32_16x16x32_bf16 v[58:61], v[138:141], v[146:149], v[58:61]
	v_mfma_f32_16x16x32_bf16 v[46:49], v[130:133], v[154:157], v[46:49]
	v_mfma_f32_16x16x32_bf16 v[42:45], v[138:141], v[154:157], v[42:45]
	v_mfma_f32_16x16x32_bf16 v[30:33], v[130:133], v[172:175], v[30:33]
	v_mfma_f32_16x16x32_bf16 v[26:29], v[138:141], v[172:175], v[26:29]
	v_mfma_f32_16x16x32_bf16 v[14:17], v[130:133], v[180:183], v[14:17]
	v_mfma_f32_16x16x32_bf16 v[10:13], v[138:141], v[180:183], v[10:13]
	v_mfma_f32_16x16x32_bf16 v[62:65], v[134:137], v[150:153], v[62:65]
	v_mfma_f32_16x16x32_bf16 v[58:61], v[142:145], v[150:153], v[58:61]
	v_mfma_f32_16x16x32_bf16 v[46:49], v[134:137], v[168:171], v[46:49]
	v_mfma_f32_16x16x32_bf16 v[42:45], v[142:145], v[168:171], v[42:45]
	v_mfma_f32_16x16x32_bf16 v[30:33], v[134:137], v[176:179], v[30:33]
	v_mfma_f32_16x16x32_bf16 v[26:29], v[142:145], v[176:179], v[26:29]
	v_mfma_f32_16x16x32_bf16 v[14:17], v[134:137], v[190:193], v[14:17]
	v_mfma_f32_16x16x32_bf16 v[10:13], v[142:145], v[190:193], v[10:13]
	s_setprio 0
	s_barrier
	s_add_u32 s22, s70, 0x40080
	s_addc_u32 s23, s71, 0
	s_add_i32 s70, s50, 0x1c000
	s_mov_b32 m0, s70
	s_nop 0
	global_load_lds_dwordx4 v0, s[22:23]
	s_add_i32 m0, s70, 0x2000
	s_nop 0
	global_load_lds_dwordx4 v162, s[22:23]
	s_waitcnt vmcnt(6)
	s_barrier
; #define PG8_MMA(ai, bj, At, Bt) do { __builtin_amdgcn_s_setprio(1); _Pragma("unroll") for (int m = 0; m < 4; ++m) _Pragma("unroll") for (int n = 0; n < 2; ++n) _Pragma("unroll") for (int k = 0; k < 2; ++k) \
;         acc[ai][bj][m][n] = __builtin_amdgcn_mfma_f32_16x16x32_bf16(Bt[n][k], At[m][k], acc[ai][bj][m][n], 0, 0, 0); __builtin_amdgcn_s_setprio(0); } while (0)
; #define PG8_WAIT_V(n) asm volatile("s_waitcnt vmcnt(" #n ")" ::: "memory")
; #define PG8_BAR __builtin_amdgcn_s_barrier()
; template <class Epi>
; __device__ __forceinline__ void gemm_phase(LAS unsigned char* lds, const Gemm g, const StaticOrder& S, const Epi& E) {
;     ...
;             PG8_WAIT_V(6); PG8_BAR; PG8_MMA(1, 1, At, B1); PG8_BAR;
;         }
;         if constexpr (Epi::HAS_PRE) { E(acc, cur, wr, wc, fr, fq, pre); if (has_next) E.pre(pre, nxt, wr, fr); } else E(acc, cur, wr, wc, fr, fq);
;     __device__ __forceinline__ void operator()(const Acc& acc, const Unit& u, int wr, int wc, int fr, int fq) const {
;     ...
;         if (u.split) {
;             float* pt = part + (size_t)(u.split - 1) * 256 * DM;
; #pragma unroll
;             for (int ai = 0; ai < 2; ++ai)
; #pragma unroll
;                 for (int m = 0; m < 4; ++m)
; #pragma unroll
;                     for (int bj = 0; bj < 2; ++bj)
; #pragma unroll
;                         for (int n = 0; n < 2; ++n) *(f32x4*)(pt + (size_t)(wr * 64 + fr + ai * 128 + m * 16) * DM + col0 + bj * 128 + n * 4) = acc[ai][bj][m][n] * sc;
;             return; }
	s_setprio 1
	v_mfma_f32_16x16x32_bf16 v[54:57], v[202:205], v[146:149], v[54:57]
	ds_read_b128 v[130:133], v218
	v_mfma_f32_16x16x32_bf16 v[50:53], v[210:213], v[146:149], v[50:53]
	ds_read_b128 v[134:137], v218 offset:1024
	v_mfma_f32_16x16x32_bf16 v[38:41], v[202:205], v[154:157], v[38:41]
	ds_read_b128 v[138:141], v218 offset:2048
	v_mfma_f32_16x16x32_bf16 v[34:37], v[210:213], v[154:157], v[34:37]
	ds_read_b128 v[142:145], v218 offset:3072
	v_mfma_f32_16x16x32_bf16 v[22:25], v[202:205], v[172:175], v[22:25]
	v_mfma_f32_16x16x32_bf16 v[18:21], v[210:213], v[172:175], v[18:21]
	v_mfma_f32_16x16x32_bf16 v[6:9], v[202:205], v[180:183], v[6:9]
	v_mfma_f32_16x16x32_bf16 v[2:5], v[210:213], v[180:183], v[2:5]
	v_mfma_f32_16x16x32_bf16 v[54:57], v[206:209], v[150:153], v[54:57]
	v_mfma_f32_16x16x32_bf16 v[50:53], v[214:217], v[150:153], v[50:53]
	v_mfma_f32_16x16x32_bf16 v[38:41], v[206:209], v[168:171], v[38:41]
	v_mfma_f32_16x16x32_bf16 v[34:37], v[214:217], v[168:171], v[34:37]
	v_mfma_f32_16x16x32_bf16 v[22:25], v[206:209], v[176:179], v[22:25]
	v_mfma_f32_16x16x32_bf16 v[18:21], v[214:217], v[176:179], v[18:21]
	v_mfma_f32_16x16x32_bf16 v[6:9], v[206:209], v[190:193], v[6:9]
	v_mfma_f32_16x16x32_bf16 v[2:5], v[214:217], v[190:193], v[2:5]
	s_setprio 0
	s_add_u32 s68, s68, 0x100
	s_addc_u32 s69, s69, 0
	s_add_u32 s67, s67, 0x100
	s_addc_u32 s97, s97, 0
	s_cmp_ge_i32 vcc_lo, s30
	s_mov_b32 s70, vcc_lo
	s_barrier
	s_cbranch_scc0 .LBB0_209
	s_waitcnt lgkmcnt(0)
	s_lshl_b32 s22, s42, 8
	v_mov_b32_e32 v133, v186
	v_mov_b32_e32 v132, v187
	s_or_b32 s22, s22, s82
	s_cmp_lg_u32 s66, 0
	v_lshl_add_u32 v168, v132, 3, s22
	v_add_u32_e32 v130, s81, v133
	v_ashrrev_i32_e32 v169, 31, v168
	s_cbranch_scc0 .LBB0_212
	s_ashr_i32 s67, s66, 31
	s_lshl_b64 s[66:67], s[66:67], 20
	s_add_u32 s66, s19, s66
	s_addc_u32 s67, s80, s67
	v_ashrrev_i32_e32 v131, 31, v130
	v_lshl_add_u64 v[134:135], v[168:169], 2, s[66:67]
	v_lshlrev_b64 v[136:137], 12, v[130:131]
	s_mov_b32 s22, 0xfff00000
	v_lshl_add_u64 v[134:135], v[134:135], 0, v[136:137]
	s_mov_b32 s23, -1
	v_lshl_add_u64 v[136:137], v[134:135], 0, s[22:23]
	v_add_co_u32_e32 v138, vcc, s83, v134
	s_mov_b32 s22, 0xfff10000
	s_nop 0
	v_addc_co_u32_e32 v139, vcc, -1, v135, vcc
	s_mov_b32 s23, -1
	global_store_dwordx4 v[138:139], v[126:129], off
	global_store_dwordx4 v[136:137], v[122:125], off offset:16
	global_store_dwordx4 v[136:137], v[118:121], off offset:512
	global_store_dwordx4 v[136:137], v[114:117], off offset:528
	v_lshl_add_u64 v[136:137], v[134:135], 0, s[22:23]
	v_add_co_u32_e32 v138, vcc, s1, v134
	s_mov_b32 s22, 0xfff20000
	s_nop 0
	v_addc_co_u32_e32 v139, vcc, -1, v135, vcc
	s_mov_b32 s23, -1
	global_store_dwordx4 v[138:139], v[110:113], off
	global_store_dwordx4 v[136:137], v[106:109], off offset:16
	global_store_dwordx4 v[136:137], v[102:105], off offset:512
	global_store_dwordx4 v[136:137], v[98:101], off offset:528
	v_lshl_add_u64 v[136:137], v[134:135], 0, s[22:23]
	s_mov_b32 s22, 0xfff20000
	v_add_co_u32_e32 v138, vcc, s22, v134
	s_mov_b32 s22, 0xfff30000
	s_nop 0
	v_addc_co_u32_e32 v139, vcc, -1, v135, vcc
	s_mov_b32 s23, -1
	global_store_dwordx4 v[138:139], v[94:97], off
	global_store_dwordx4 v[136:137], v[90:93], off offset:16
	global_store_dwordx4 v[136:137], v[86:89], off offset:512
	global_store_dwordx4 v[136:137], v[82:85], off offset:528
	v_lshl_add_u64 v[136:137], v[134:135], 0, s[22:23]
	s_mov_b32 s22, 0xfff30000
	v_add_co_u32_e32 v138, vcc, s22, v134
	s_mov_b32 s22, 0xfff80000
	s_nop 0
	v_addc_co_u32_e32 v139, vcc, -1, v135, vcc
	s_mov_b32 s23, -1
	global_store_dwordx4 v[138:139], v[78:81], off
	global_store_dwordx4 v[136:137], v[74:77], off offset:16
	global_store_dwordx4 v[136:137], v[70:73], off offset:512
	global_store_dwordx4 v[136:137], v[66:69], off offset:528
	v_lshl_add_u64 v[136:137], v[134:135], 0, s[22:23]
	s_mov_b32 s22, 0xfff80000
	v_add_co_u32_e32 v138, vcc, s22, v134
	s_mov_b32 s22, 0xfff90000
	s_nop 0
	v_addc_co_u32_e32 v139, vcc, -1, v135, vcc
	s_mov_b32 s23, -1
	global_store_dwordx4 v[138:139], v[62:65], off
	global_store_dwordx4 v[136:137], v[58:61], off offset:16
	global_store_dwordx4 v[136:137], v[54:57], off offset:512
	global_store_dwordx4 v[136:137], v[50:53], off offset:528
	v_lshl_add_u64 v[136:137], v[134:135], 0, s[22:23]
	s_mov_b32 s22, 0xfff90000
	v_add_co_u32_e32 v138, vcc, s22, v134
	s_mov_b32 s22, 0xfffa0000
	s_nop 0
	v_addc_co_u32_e32 v139, vcc, -1, v135, vcc
	s_mov_b32 s23, -1
	global_store_dwordx4 v[138:139], v[46:49], off
	global_store_dwordx4 v[136:137], v[42:45], off offset:16
	global_store_dwordx4 v[136:137], v[38:41], off offset:512
	global_store_dwordx4 v[136:137], v[34:37], off offset:528
	v_lshl_add_u64 v[136:137], v[134:135], 0, s[22:23]
	s_mov_b32 s22, 0xfffa0000
	v_add_co_u32_e32 v138, vcc, s22, v134
	s_mov_b32 s22, 0xfffb0000
	s_nop 0
	v_addc_co_u32_e32 v139, vcc, -1, v135, vcc
	s_mov_b32 s23, -1
	global_store_dwordx4 v[138:139], v[30:33], off
	global_store_dwordx4 v[136:137], v[26:29], off offset:16
	global_store_dwordx4 v[136:137], v[22:25], off offset:512
	global_store_dwordx4 v[136:137], v[18:21], off offset:528
	v_lshl_add_u64 v[136:137], v[134:135], 0, s[22:23]
	v_add_co_u32_e32 v134, vcc, 0xfffb0000, v134
	s_mov_b64 s[66:67], 0
	s_nop 0
	v_addc_co_u32_e32 v135, vcc, -1, v135, vcc
	global_store_dwordx4 v[134:135], v[14:17], off
	global_store_dwordx4 v[136:137], v[10:13], off offset:16
	global_store_dwordx4 v[136:137], v[6:9], off offset:512
	global_store_dwordx4 v[136:137], v[2:5], off offset:528
	s_branch .LBB0_213

; #define PG8_STAGE(bufoff, gbase, voff) do { _Pragma("unroll") for (int _i = 0; _i < 2; ++_i) \
;         __builtin_amdgcn_global_load_lds((const unsigned*)((const char*)(gbase) + (voff)[_i]), (LAS unsigned*)(lds + (bufoff) + ldsw + _i * 8192), 16, 0, 0); } while (0)
; #define PG8_LDA(dst, b, h) do { _Pragma("unroll") for (int m = 0; m < 4; ++m) _Pragma("unroll") for (int k = 0; k < 2; ++k) dst[m][k] = *(const LAS bf16x8*)(lds + PG8_SA(b, h) + aoff + m * 2048 + k * 1024); } while (0)
; #define PG8_LDB(dst, b, h) do { _Pragma("unroll") for (int n = 0; n < 2; ++n) _Pragma("unroll") for (int k = 0; k < 2; ++k) dst[n][k] = *(const LAS bf16x8*)(lds + PG8_SB(b, h) + boff + n * 2048 + k * 1024); } while (0)
; #define PG8_MMA(ai, bj, At, Bt) do { __builtin_amdgcn_s_setprio(1); _Pragma("unroll") for (int m = 0; m < 4; ++m) _Pragma("unroll") for (int n = 0; n < 2; ++n) _Pragma("unroll") for (int k = 0; k < 2; ++k) \
;         acc[ai][bj][m][n] = __builtin_amdgcn_mfma_f32_16x16x32_bf16(Bt[n][k], At[m][k], acc[ai][bj][m][n], 0, 0, 0); __builtin_amdgcn_s_setprio(0); } while (0)
; template <class Epi>
; __device__ __forceinline__ void gemm_phase(LAS unsigned char* lds, const Gemm g, const StaticOrder& S, const Epi& E) {
;     ...
;         const bool has_next = S.next(ui + 1, nxt);
;         const char* nA = has_next ? (const char*)(nxt.alt ? g.A2 : g.A) + (size_t)nxt.pm * tA + (size_t)nxt.k0 * 2 : cA; const char* nB = has_next ? (const char*)(nxt.alt ? g.Bt2 : g.Bt) + (size_t)nxt.pn * tB + (size_t)nxt.k0 * 2 : cB;
;         const int nt = cur.nt;
;         for (int t = 0; t < nt; t += 2) {
;             const bool last = (t == nt - 2);
;             const char* a1 = cA + (size_t)(t + 1) * kstep;
;             const char* a2 = last ? nA : cA + (size_t)(t + 2) * kstep; const char* b2 = last ? nB : cB + (size_t)(t + 2) * kstep;
;             const char* a3 = a2 + kstep; const char* b3 = b2 + kstep;
;             PG8_LDB(B0, 0, 0); PG8_SCHED; PG8_LDA(At, 0, 0); PG8_STAGE(PG8_SA(1, 1), a1 + hA, voffA);
;             PG8_WAIT_L(8); PG8_BAR; PG8_WAIT_L(0); PG8_MMA(0, 0, At, B0); PG8_BAR; PG8_SCHED;
;             PG8_LDB(B1, 0, 1); PG8_STAGE(PG8_SB(0, 0), b2, voffB);
;             PG8_BAR; PG8_WAIT_L(0); PG8_MMA(0, 1, At, B1); PG8_BAR;
;             PG8_LDA(At, 0, 1); PG8_STAGE(PG8_SA(0, 0), a2, voffA);
;             PG8_BAR; PG8_WAIT_L(0); PG8_MMA(1, 0, At, B0); PG8_BAR; PG8_SCHED;
.LBB0_262:
	s_cmp_eq_u32 s29, 0
	s_cselect_b32 s22, s16, s80
	s_cselect_b32 s23, s15, s19
	s_ashr_i32 s59, s58, 31
	s_lshl_b64 s[62:63], s[58:59], 18
	s_add_u32 s62, s23, s62
	s_addc_u32 s63, s22, s63
	s_and_b64 s[66:67], s[40:41], exec
	s_cselect_b32 s43, s63, s65
	s_cselect_b32 s49, s62, s64
	s_add_u32 s59, s64, 0x100
	s_addc_u32 s97, s65, 0
	s_mov_b32 vcc_lo, -2
	v_add_u32_e32 v0, 0x10000, v241
	ds_read_b128 v[132:135], v0
	ds_read_b128 v[136:139], v0 offset:1024
	ds_read_b128 v[140:143], v0 offset:2048
	ds_read_b128 v[144:147], v0 offset:3072
.LBB0_263:
	s_add_u32 s64, s44, 0x100
	s_addc_u32 s65, s45, 0
	s_add_i32 s22, 0, 0x10000
	s_cmp_eq_u32 vcc_lo, 4
	s_cselect_b32 s69, s61, s65
	s_cselect_b32 s68, s60, s64
	s_cselect_b32 s67, s43, s97
	s_cselect_b32 s66, s49, s59
	s_add_i32 m0, s70, 0xc000
	ds_read_b128 v[148:151], v242
	ds_read_b128 v[152:155], v242 offset:1024
	ds_read_b128 v[156:159], v242 offset:2048
	ds_read_b128 v[160:163], v242 offset:3072
	ds_read_b128 v[164:167], v242 offset:4096
	ds_read_b128 v[168:171], v242 offset:5120
	ds_read_b128 v[172:175], v242 offset:6144
	ds_read_b128 v[176:179], v242 offset:7168
	global_load_lds_dwordx4 v210, s[44:45]
	s_add_i32 m0, s70, 0xe000
	s_nop 0
	global_load_lds_dwordx4 v212, s[44:45]
	s_waitcnt lgkmcnt(8)
	s_barrier
	s_waitcnt lgkmcnt(0)
	s_setprio 1
	v_mfma_f32_16x16x32_bf16 v[2:5], v[132:135], v[148:151], v[4:7]
	v_mfma_f32_16x16x32_bf16 v[6:9], v[140:143], v[148:151], v[8:11]
	v_mfma_f32_16x16x32_bf16 v[128:131], v[132:135], v[156:159], v[128:131]
	v_mfma_f32_16x16x32_bf16 v[124:127], v[140:143], v[156:159], v[124:127]
	v_mfma_f32_16x16x32_bf16 v[120:123], v[132:135], v[164:167], v[120:123]
	v_mfma_f32_16x16x32_bf16 v[116:119], v[140:143], v[164:167], v[116:119]
	v_mfma_f32_16x16x32_bf16 v[112:115], v[132:135], v[172:175], v[112:115]
	v_mfma_f32_16x16x32_bf16 v[108:111], v[140:143], v[172:175], v[108:111]
	v_mfma_f32_16x16x32_bf16 v[2:5], v[136:139], v[152:155], v[2:5]
	v_mfma_f32_16x16x32_bf16 v[8:11], v[144:147], v[152:155], v[6:9]
	v_mfma_f32_16x16x32_bf16 v[128:131], v[136:139], v[160:163], v[128:131]
	v_mfma_f32_16x16x32_bf16 v[124:127], v[144:147], v[160:163], v[124:127]
	v_mfma_f32_16x16x32_bf16 v[120:123], v[136:139], v[168:171], v[120:123]
	v_mfma_f32_16x16x32_bf16 v[116:119], v[144:147], v[168:171], v[116:119]
	v_mfma_f32_16x16x32_bf16 v[112:115], v[136:139], v[176:179], v[112:115]
	v_mfma_f32_16x16x32_bf16 v[108:111], v[144:147], v[176:179], v[108:111]
	s_setprio 0
	s_barrier
	s_add_i32 s23, 0, 0x14000
	s_add_i32 s22, s22, s53
	s_mov_b32 m0, s22
	ds_read_b128 v[180:183], v0 offset:16384
	ds_read_b128 v[184:187], v0 offset:17408
	ds_read_b128 v[188:191], v0 offset:18432
	ds_read_b128 v[192:195], v0 offset:19456
	global_load_lds_dwordx4 v204, s[66:67]
	s_add_i32 m0, s22, 0x2000
	s_nop 0
	global_load_lds_dwordx4 v208, s[66:67]
	s_barrier
	s_waitcnt lgkmcnt(0)
	s_setprio 1
	v_mfma_f32_16x16x32_bf16 v[104:107], v[180:183], v[148:151], v[104:107]
	v_mfma_f32_16x16x32_bf16 v[100:103], v[188:191], v[148:151], v[100:103]
	v_mfma_f32_16x16x32_bf16 v[96:99], v[180:183], v[156:159], v[96:99]
	v_mfma_f32_16x16x32_bf16 v[92:95], v[188:191], v[156:159], v[92:95]
	v_mfma_f32_16x16x32_bf16 v[88:91], v[180:183], v[164:167], v[88:91]
	v_mfma_f32_16x16x32_bf16 v[84:87], v[188:191], v[164:167], v[84:87]
	v_mfma_f32_16x16x32_bf16 v[80:83], v[180:183], v[172:175], v[80:83]
	v_mfma_f32_16x16x32_bf16 v[76:79], v[188:191], v[172:175], v[76:79]
	v_mfma_f32_16x16x32_bf16 v[104:107], v[184:187], v[152:155], v[104:107]
	v_mfma_f32_16x16x32_bf16 v[100:103], v[192:195], v[152:155], v[100:103]
	v_mfma_f32_16x16x32_bf16 v[96:99], v[184:187], v[160:163], v[96:99]
	v_mfma_f32_16x16x32_bf16 v[92:95], v[192:195], v[160:163], v[92:95]
	v_mfma_f32_16x16x32_bf16 v[88:91], v[184:187], v[168:171], v[88:91]
	v_mfma_f32_16x16x32_bf16 v[84:87], v[192:195], v[168:171], v[84:87]
	v_mfma_f32_16x16x32_bf16 v[80:83], v[184:187], v[176:179], v[80:83]
	v_mfma_f32_16x16x32_bf16 v[76:79], v[192:195], v[176:179], v[76:79]
	s_setprio 0
	s_mov_b32 m0, s70
	s_barrier
	ds_read_b128 v[148:151], v242 offset:16384
	ds_read_b128 v[152:155], v242 offset:17408
	ds_read_b128 v[156:159], v242 offset:18432
	ds_read_b128 v[160:163], v242 offset:19456
	ds_read_b128 v[164:167], v242 offset:20480
	ds_read_b128 v[168:171], v242 offset:21504
	ds_read_b128 v[172:175], v242 offset:22528
	ds_read_b128 v[176:179], v242 offset:23552
	global_load_lds_dwordx4 v202, s[68:69]
	s_mov_b32 m0, s71
	s_nop 0
	global_load_lds_dwordx4 v206, s[68:69]
	s_waitcnt vmcnt(8)
	s_barrier
	s_waitcnt lgkmcnt(0)
	s_setprio 1
	v_mfma_f32_16x16x32_bf16 v[72:75], v[132:135], v[148:151], v[72:75]
	v_mfma_f32_16x16x32_bf16 v[68:71], v[140:143], v[148:151], v[68:71]
	v_mfma_f32_16x16x32_bf16 v[64:67], v[132:135], v[156:159], v[64:67]
	v_mfma_f32_16x16x32_bf16 v[60:63], v[140:143], v[156:159], v[60:63]
	v_mfma_f32_16x16x32_bf16 v[56:59], v[132:135], v[164:167], v[56:59]
	v_mfma_f32_16x16x32_bf16 v[52:55], v[140:143], v[164:167], v[52:55]
	v_mfma_f32_16x16x32_bf16 v[48:51], v[132:135], v[172:175], v[48:51]
	v_mfma_f32_16x16x32_bf16 v[44:47], v[140:143], v[172:175], v[44:47]
	v_mfma_f32_16x16x32_bf16 v[72:75], v[136:139], v[152:155], v[72:75]
	v_mfma_f32_16x16x32_bf16 v[68:71], v[144:147], v[152:155], v[68:71]
	v_mfma_f32_16x16x32_bf16 v[64:67], v[136:139], v[160:163], v[64:67]
	v_mfma_f32_16x16x32_bf16 v[60:63], v[144:147], v[160:163], v[60:63]
	v_mfma_f32_16x16x32_bf16 v[56:59], v[136:139], v[168:171], v[56:59]
	v_mfma_f32_16x16x32_bf16 v[52:55], v[144:147], v[168:171], v[52:55]
	v_mfma_f32_16x16x32_bf16 v[48:51], v[136:139], v[176:179], v[48:51]
	v_mfma_f32_16x16x32_bf16 v[44:47], v[144:147], v[176:179], v[44:47]
	s_setprio 0
	s_barrier
; #define PG8_STAGE(bufoff, gbase, voff) do { _Pragma("unroll") for (int _i = 0; _i < 2; ++_i) \
;         __builtin_amdgcn_global_load_lds((const unsigned*)((const char*)(gbase) + (voff)[_i]), (LAS unsigned*)(lds + (bufoff) + ldsw + _i * 8192), 16, 0, 0); } while (0)
; #define PG8_LDA(dst, b, h) do { _Pragma("unroll") for (int m = 0; m < 4; ++m) _Pragma("unroll") for (int k = 0; k < 2; ++k) dst[m][k] = *(const LAS bf16x8*)(lds + PG8_SA(b, h) + aoff + m * 2048 + k * 1024); } while (0)
; #define PG8_LDB(dst, b, h) do { _Pragma("unroll") for (int n = 0; n < 2; ++n) _Pragma("unroll") for (int k = 0; k < 2; ++k) dst[n][k] = *(const LAS bf16x8*)(lds + PG8_SB(b, h) + boff + n * 2048 + k * 1024); } while (0)
; #define PG8_MMA(ai, bj, At, Bt) do { __builtin_amdgcn_s_setprio(1); _Pragma("unroll") for (int m = 0; m < 4; ++m) _Pragma("unroll") for (int n = 0; n < 2; ++n) _Pragma("unroll") for (int k = 0; k < 2; ++k) \
;         acc[ai][bj][m][n] = __builtin_amdgcn_mfma_f32_16x16x32_bf16(Bt[n][k], At[m][k], acc[ai][bj][m][n], 0, 0, 0); __builtin_amdgcn_s_setprio(0); } while (0)
; #define PG8_WAIT_V(n) asm volatile("s_waitcnt vmcnt(" #n ")" ::: "memory")
; #define PG8_WAIT_L(n) asm volatile("s_waitcnt lgkmcnt(" #n ")" ::: "memory")
; #define PG8_BAR __builtin_amdgcn_s_barrier()
; #define PG8_SCHED __builtin_amdgcn_sched_barrier(0)
; template <class Epi>
; __device__ __forceinline__ void gemm_phase(LAS unsigned char* lds, const Gemm g, const StaticOrder& S, const Epi& E) {
;     ...
;             PG8_STAGE(PG8_SB(0, 1), b2 + hB, voffB);
;             PG8_WAIT_V(6); PG8_BAR; PG8_MMA(1, 1, At, B1); PG8_BAR;
;             PG8_LDB(B0, 1, 0); PG8_SCHED; PG8_LDA(At, 1, 0); PG8_STAGE(PG8_SA(0, 1), a2 + hA, voffA);
;             PG8_WAIT_L(8); PG8_BAR; PG8_WAIT_L(0); PG8_MMA(0, 0, At, B0); PG8_BAR; PG8_SCHED;
;             PG8_LDB(B1, 1, 1); PG8_STAGE(PG8_SB(1, 0), b3, voffB);
;             PG8_BAR; PG8_WAIT_L(0); PG8_MMA(0, 1, At, B1); PG8_BAR;
	s_add_u32 s44, s66, 0x20000
	s_addc_u32 s45, s67, 0
	s_add_i32 s22, s23, s53
	s_mov_b32 m0, s22
	s_nop 0
	global_load_lds_dwordx4 v204, s[44:45]
	s_add_i32 m0, s22, 0x2000
	s_nop 0
	global_load_lds_dwordx4 v208, s[44:45]
	s_waitcnt vmcnt(6)
	s_barrier
	s_setprio 1
	v_mfma_f32_16x16x32_bf16 v[40:43], v[180:183], v[148:151], v[40:43]
	ds_read_b128 v[132:135], v0 offset:32768
	v_mfma_f32_16x16x32_bf16 v[36:39], v[188:191], v[148:151], v[36:39]
	ds_read_b128 v[136:139], v0 offset:33792
	v_mfma_f32_16x16x32_bf16 v[32:35], v[180:183], v[156:159], v[32:35]
	ds_read_b128 v[140:143], v0 offset:34816
	v_mfma_f32_16x16x32_bf16 v[28:31], v[188:191], v[156:159], v[28:31]
	ds_read_b128 v[144:147], v0 offset:35840
	v_mfma_f32_16x16x32_bf16 v[24:27], v[180:183], v[164:167], v[24:27]
	v_mfma_f32_16x16x32_bf16 v[20:23], v[188:191], v[164:167], v[20:23]
	v_mfma_f32_16x16x32_bf16 v[16:19], v[180:183], v[172:175], v[16:19]
	v_mfma_f32_16x16x32_bf16 v[12:15], v[188:191], v[172:175], v[12:15]
	v_mfma_f32_16x16x32_bf16 v[40:43], v[184:187], v[152:155], v[40:43]
	v_mfma_f32_16x16x32_bf16 v[36:39], v[192:195], v[152:155], v[36:39]
	v_mfma_f32_16x16x32_bf16 v[32:35], v[184:187], v[160:163], v[32:35]
	v_mfma_f32_16x16x32_bf16 v[28:31], v[192:195], v[160:163], v[28:31]
	v_mfma_f32_16x16x32_bf16 v[24:27], v[184:187], v[168:171], v[24:27]
	v_mfma_f32_16x16x32_bf16 v[20:23], v[192:195], v[168:171], v[20:23]
	v_mfma_f32_16x16x32_bf16 v[16:19], v[184:187], v[176:179], v[16:19]
	v_mfma_f32_16x16x32_bf16 v[12:15], v[192:195], v[176:179], v[12:15]
	s_setprio 0
	s_add_i32 s22, 0, 0x18000
	s_barrier
	s_add_u32 s44, s68, 0x110000
	s_addc_u32 s45, s69, 0
	s_mov_b32 m0, s74
	ds_read_b128 v[148:151], v242 offset:32768
	ds_read_b128 v[152:155], v242 offset:33792
	ds_read_b128 v[156:159], v242 offset:34816
	ds_read_b128 v[160:163], v242 offset:35840
	ds_read_b128 v[164:167], v242 offset:36864
	ds_read_b128 v[168:171], v242 offset:37888
	ds_read_b128 v[172:175], v242 offset:38912
	ds_read_b128 v[176:179], v242 offset:39936
	global_load_lds_dwordx4 v202, s[44:45]
	s_mov_b32 m0, s75
	s_nop 0
	global_load_lds_dwordx4 v206, s[44:45]
	s_waitcnt lgkmcnt(8)
	s_barrier
	s_waitcnt lgkmcnt(0)
	s_setprio 1
	v_mfma_f32_16x16x32_bf16 v[2:5], v[132:135], v[148:151], v[2:5]
	v_mfma_f32_16x16x32_bf16 v[8:11], v[140:143], v[148:151], v[8:11]
	v_mfma_f32_16x16x32_bf16 v[128:131], v[132:135], v[156:159], v[128:131]
	v_mfma_f32_16x16x32_bf16 v[124:127], v[140:143], v[156:159], v[124:127]
	v_mfma_f32_16x16x32_bf16 v[120:123], v[132:135], v[164:167], v[120:123]
	v_mfma_f32_16x16x32_bf16 v[116:119], v[140:143], v[164:167], v[116:119]
	v_mfma_f32_16x16x32_bf16 v[112:115], v[132:135], v[172:175], v[112:115]
	v_mfma_f32_16x16x32_bf16 v[108:111], v[140:143], v[172:175], v[108:111]
	v_mfma_f32_16x16x32_bf16 v[4:7], v[136:139], v[152:155], v[2:5]
	v_mfma_f32_16x16x32_bf16 v[8:11], v[144:147], v[152:155], v[8:11]
	v_mfma_f32_16x16x32_bf16 v[128:131], v[136:139], v[160:163], v[128:131]
	v_mfma_f32_16x16x32_bf16 v[124:127], v[144:147], v[160:163], v[124:127]
	v_mfma_f32_16x16x32_bf16 v[120:123], v[136:139], v[168:171], v[120:123]
	v_mfma_f32_16x16x32_bf16 v[116:119], v[144:147], v[168:171], v[116:119]
	v_mfma_f32_16x16x32_bf16 v[112:115], v[136:139], v[176:179], v[112:115]
	v_mfma_f32_16x16x32_bf16 v[108:111], v[144:147], v[176:179], v[108:111]
	s_setprio 0
	s_barrier
	s_add_i32 s23, 0, 0x1c000
	s_add_i32 s22, s22, s53
	s_mov_b32 m0, s22
	ds_read_b128 v[180:183], v0 offset:49152
	ds_read_b128 v[184:187], v0 offset:50176
	ds_read_b128 v[188:191], v0 offset:51200
	ds_read_b128 v[192:195], v0 offset:52224
	s_add_u32 s100, s66, 0x80
	s_addc_u32 s101, s67, 0
	global_load_lds_dwordx4 v204, s[100:101]
	s_add_i32 m0, s22, 0x2000
	s_nop 0
	global_load_lds_dwordx4 v208, s[100:101]
	s_barrier
	s_waitcnt lgkmcnt(0)
	s_setprio 1
	v_mfma_f32_16x16x32_bf16 v[104:107], v[180:183], v[148:151], v[104:107]
	v_mfma_f32_16x16x32_bf16 v[100:103], v[188:191], v[148:151], v[100:103]
	v_mfma_f32_16x16x32_bf16 v[96:99], v[180:183], v[156:159], v[96:99]
	v_mfma_f32_16x16x32_bf16 v[92:95], v[188:191], v[156:159], v[92:95]
	v_mfma_f32_16x16x32_bf16 v[88:91], v[180:183], v[164:167], v[88:91]
	v_mfma_f32_16x16x32_bf16 v[84:87], v[188:191], v[164:167], v[84:87]
	v_mfma_f32_16x16x32_bf16 v[80:83], v[180:183], v[172:175], v[80:83]
	v_mfma_f32_16x16x32_bf16 v[76:79], v[188:191], v[172:175], v[76:79]
	v_mfma_f32_16x16x32_bf16 v[104:107], v[184:187], v[152:155], v[104:107]
	v_mfma_f32_16x16x32_bf16 v[100:103], v[192:195], v[152:155], v[100:103]
	v_mfma_f32_16x16x32_bf16 v[96:99], v[184:187], v[160:163], v[96:99]
	v_mfma_f32_16x16x32_bf16 v[92:95], v[192:195], v[160:163], v[92:95]
	v_mfma_f32_16x16x32_bf16 v[88:91], v[184:187], v[168:171], v[88:91]
	v_mfma_f32_16x16x32_bf16 v[84:87], v[192:195], v[168:171], v[84:87]
	v_mfma_f32_16x16x32_bf16 v[80:83], v[184:187], v[176:179], v[80:83]
	v_mfma_f32_16x16x32_bf16 v[76:79], v[192:195], v[176:179], v[76:79]
	s_setprio 0
	s_mov_b32 m0, s30
	s_barrier
; #define PG8_STAGE(bufoff, gbase, voff) do { _Pragma("unroll") for (int _i = 0; _i < 2; ++_i) \
;         __builtin_amdgcn_global_load_lds((const unsigned*)((const char*)(gbase) + (voff)[_i]), (LAS unsigned*)(lds + (bufoff) + ldsw + _i * 8192), 16, 0, 0); } while (0)
; #define PG8_LDA(dst, b, h) do { _Pragma("unroll") for (int m = 0; m < 4; ++m) _Pragma("unroll") for (int k = 0; k < 2; ++k) dst[m][k] = *(const LAS bf16x8*)(lds + PG8_SA(b, h) + aoff + m * 2048 + k * 1024); } while (0)
; #define PG8_MMA(ai, bj, At, Bt) do { __builtin_amdgcn_s_setprio(1); _Pragma("unroll") for (int m = 0; m < 4; ++m) _Pragma("unroll") for (int n = 0; n < 2; ++n) _Pragma("unroll") for (int k = 0; k < 2; ++k) \
;         acc[ai][bj][m][n] = __builtin_amdgcn_mfma_f32_16x16x32_bf16(Bt[n][k], At[m][k], acc[ai][bj][m][n], 0, 0, 0); __builtin_amdgcn_s_setprio(0); } while (0)
; #define PG8_WAIT_V(n) asm volatile("s_waitcnt vmcnt(" #n ")" ::: "memory")
; #define PG8_WAIT_L(n) asm volatile("s_waitcnt lgkmcnt(" #n ")" ::: "memory")
; #define PG8_BAR __builtin_amdgcn_s_barrier()
; #define PG8_SCHED __builtin_amdgcn_sched_barrier(0)
; template <class Epi>
; __device__ __forceinline__ void gemm_phase(LAS unsigned char* lds, const Gemm g, const StaticOrder& S, const Epi& E) {
;     ...
;             PG8_LDA(At, 1, 1); PG8_STAGE(PG8_SA(1, 0), a3, voffA);
;             PG8_BAR; PG8_WAIT_L(0); PG8_MMA(1, 0, At, B0); PG8_BAR; PG8_SCHED;
;             PG8_STAGE(PG8_SB(1, 1), b3 + hB, voffB);
;             PG8_WAIT_V(6); PG8_BAR; PG8_MMA(1, 1, At, B1); PG8_BAR;
;         }
;         if constexpr (Epi::HAS_PRE) { E(acc, cur, wr, wc, fr, fq, pre); if (has_next) E.pre(pre, nxt, wr, fr); } else E(acc, cur, wr, wc, fr, fq);
;     __device__ __forceinline__ void operator()(Acc& acc, const Unit& u, int wr, int wc, int fr, int fq) const {
;     ...
;                 for (int bj = 0; bj < 2; ++bj) { const size_t off = (size_t)(row0 + ai * 128 + m * 16) * NPROJ + col0 + bj * 128;
;                     bv[m][bj] = *(const u32x4*)(gb + off); if (u.alt == 0) av[m][bj] = *(const u32x4*)(ga + off); }
	ds_read_b128 v[148:151], v242 offset:49152
	ds_read_b128 v[152:155], v242 offset:50176
	ds_read_b128 v[156:159], v242 offset:51200
	ds_read_b128 v[160:163], v242 offset:52224
	ds_read_b128 v[164:167], v242 offset:53248
	ds_read_b128 v[168:171], v242 offset:54272
	ds_read_b128 v[172:175], v242 offset:55296
	ds_read_b128 v[176:179], v242 offset:56320
	s_add_u32 s100, s68, 0x80
	s_addc_u32 s101, s69, 0
	global_load_lds_dwordx4 v202, s[100:101]
	s_mov_b32 m0, s46
	s_nop 0
	global_load_lds_dwordx4 v206, s[100:101]
	s_waitcnt vmcnt(8)
	s_barrier
	s_waitcnt lgkmcnt(0)
	s_setprio 1
	v_mfma_f32_16x16x32_bf16 v[72:75], v[132:135], v[148:151], v[72:75]
	v_mfma_f32_16x16x32_bf16 v[68:71], v[140:143], v[148:151], v[68:71]
	v_mfma_f32_16x16x32_bf16 v[64:67], v[132:135], v[156:159], v[64:67]
	v_mfma_f32_16x16x32_bf16 v[60:63], v[140:143], v[156:159], v[60:63]
	v_mfma_f32_16x16x32_bf16 v[56:59], v[132:135], v[164:167], v[56:59]
	v_mfma_f32_16x16x32_bf16 v[52:55], v[140:143], v[164:167], v[52:55]
	v_mfma_f32_16x16x32_bf16 v[48:51], v[132:135], v[172:175], v[48:51]
	v_mfma_f32_16x16x32_bf16 v[44:47], v[140:143], v[172:175], v[44:47]
	v_mfma_f32_16x16x32_bf16 v[72:75], v[136:139], v[152:155], v[72:75]
	v_mfma_f32_16x16x32_bf16 v[68:71], v[144:147], v[152:155], v[68:71]
	v_mfma_f32_16x16x32_bf16 v[64:67], v[136:139], v[160:163], v[64:67]
	v_mfma_f32_16x16x32_bf16 v[60:63], v[144:147], v[160:163], v[60:63]
	v_mfma_f32_16x16x32_bf16 v[56:59], v[136:139], v[168:171], v[56:59]
	v_mfma_f32_16x16x32_bf16 v[52:55], v[144:147], v[168:171], v[52:55]
	v_mfma_f32_16x16x32_bf16 v[48:51], v[136:139], v[176:179], v[48:51]
	v_mfma_f32_16x16x32_bf16 v[44:47], v[144:147], v[176:179], v[44:47]
	s_setprio 0
	s_barrier
	s_add_u32 s44, s66, 0x20080
	s_addc_u32 s45, s67, 0
	s_add_i32 s22, s23, s53
	s_mov_b32 m0, s22
	s_nop 0
	global_load_lds_dwordx4 v204, s[44:45]
	s_add_i32 m0, s22, 0x2000
	s_nop 0
	global_load_lds_dwordx4 v208, s[44:45]
	s_waitcnt vmcnt(6)
	s_barrier
	s_setprio 1
	v_mfma_f32_16x16x32_bf16 v[40:43], v[180:183], v[148:151], v[40:43]
	ds_read_b128 v[132:135], v0
	v_mfma_f32_16x16x32_bf16 v[36:39], v[188:191], v[148:151], v[36:39]
	ds_read_b128 v[136:139], v0 offset:1024
	v_mfma_f32_16x16x32_bf16 v[32:35], v[180:183], v[156:159], v[32:35]
	ds_read_b128 v[140:143], v0 offset:2048
	v_mfma_f32_16x16x32_bf16 v[28:31], v[188:191], v[156:159], v[28:31]
	ds_read_b128 v[144:147], v0 offset:3072
	v_mfma_f32_16x16x32_bf16 v[24:27], v[180:183], v[164:167], v[24:27]
	v_mfma_f32_16x16x32_bf16 v[20:23], v[188:191], v[164:167], v[20:23]
	v_mfma_f32_16x16x32_bf16 v[16:19], v[180:183], v[172:175], v[16:19]
	v_mfma_f32_16x16x32_bf16 v[12:15], v[188:191], v[172:175], v[12:15]
	v_mfma_f32_16x16x32_bf16 v[40:43], v[184:187], v[152:155], v[40:43]
	v_mfma_f32_16x16x32_bf16 v[36:39], v[192:195], v[152:155], v[36:39]
	v_mfma_f32_16x16x32_bf16 v[32:35], v[184:187], v[160:163], v[32:35]
	v_mfma_f32_16x16x32_bf16 v[28:31], v[192:195], v[160:163], v[28:31]
	v_mfma_f32_16x16x32_bf16 v[24:27], v[184:187], v[168:171], v[24:27]
	v_mfma_f32_16x16x32_bf16 v[20:23], v[192:195], v[168:171], v[20:23]
	v_mfma_f32_16x16x32_bf16 v[16:19], v[184:187], v[176:179], v[16:19]
	v_mfma_f32_16x16x32_bf16 v[12:15], v[192:195], v[176:179], v[12:15]
	s_setprio 0
	s_add_i32 vcc_lo, vcc_lo, 2
	s_add_u32 s59, s59, 0x100
	s_addc_u32 s97, s97, 0
	s_cmp_gt_u32 vcc_lo, 5
	s_mov_b64 s[44:45], s[64:65]
	s_barrier
	s_cbranch_scc0 .LBB0_263
	s_waitcnt lgkmcnt(0)
	s_lshl_b32 s22, s33, 8
	v_mov_b32_e32 v0, v240
	v_mov_b32_e32 v2, v239
	s_add_i32 s22, s22, s51
	s_nop 0
	v_add_u32_e32 v214, s22, v2
	s_lshl_b32 s22, s42, 8
	s_or_b32 s22, s22, s76
	v_lshl_add_u32 v2, v0, 3, s22
	v_ashrrev_i32_e32 v3, 31, v2
	v_mad_i64_i32 v[132:133], s[42:43], v214, s1, v[2:3]
	v_lshl_add_u64 v[134:135], v[132:133], 1, s[56:57]
	global_load_dwordx4 v[192:195], v[134:135], off
	s_cmp_eq_u32 s48, 0
	s_cselect_b64 s[42:43], -1, 0
	s_cmp_lg_u32 s48, 0
	s_cselect_b64 s[64:65], -1, 0
	s_and_b64 vcc, exec, s[64:65]
	s_cbranch_vccnz .LBB0_266
	v_lshl_add_u64 v[136:137], v[132:133], 1, s[54:55]
	global_load_dwordx4 v[160:163], v[136:137], off
